# raised wave priority (s_setprio) around the MFMA sections of the hand-written FFN-in, in-proj and residual GEMM loops
# speedup vs baseline: 1.1621x; 1.0169x over previous
.Lop_nob:
	ds_read_b128 v[204:207], v222
	ds_read_b128 v[208:211], v222 offset:2048
	ds_read_b128 v[212:215], v222 offset:4096
	ds_read_b128 v[216:219], v222 offset:6144
	ds_read_b128 a[0:3], v223
	ds_read_b128 a[4:7], v223 offset:2048
	ds_read_b128 a[8:11], v223 offset:4096
	ds_read_b128 a[12:15], v223 offset:6144
	ds_read_b128 v[136:139], v220
	ds_read_b128 v[140:143], v220 offset:2048
	ds_read_b128 v[144:147], v220 offset:4096
	ds_read_b128 v[148:151], v220 offset:6144
	ds_read_b128 v[152:155], v220 offset:8192
	ds_read_b128 v[156:159], v220 offset:10240
	s_waitcnt lgkmcnt(5)
	s_setprio 1
	v_mfma_f32_16x16x32_bf16 v[0:3], v[136:139], v[204:207], v[0:3]
	v_mfma_f32_16x16x32_bf16 v[4:7], v[136:139], v[208:211], v[4:7]
	v_mfma_f32_16x16x32_bf16 v[8:11], v[136:139], v[212:215], v[8:11]
	v_mfma_f32_16x16x32_bf16 v[12:15], v[136:139], v[216:219], v[12:15]
	s_setprio 0
	ds_read_b128 v[136:139], v221
	s_waitcnt lgkmcnt(5)
	s_setprio 1
	v_mfma_f32_16x16x32_bf16 v[16:19], v[140:143], v[204:207], v[16:19]
	v_mfma_f32_16x16x32_bf16 v[20:23], v[140:143], v[208:211], v[20:23]
	v_mfma_f32_16x16x32_bf16 v[24:27], v[140:143], v[212:215], v[24:27]
	v_mfma_f32_16x16x32_bf16 v[28:31], v[140:143], v[216:219], v[28:31]
	s_setprio 0
	ds_read_b128 v[140:143], v221 offset:2048
	s_waitcnt lgkmcnt(5)
	s_setprio 1
	v_mfma_f32_16x16x32_bf16 v[32:35], v[144:147], v[204:207], v[32:35]
	v_mfma_f32_16x16x32_bf16 v[36:39], v[144:147], v[208:211], v[36:39]
	v_mfma_f32_16x16x32_bf16 v[40:43], v[144:147], v[212:215], v[40:43]
	v_mfma_f32_16x16x32_bf16 v[44:47], v[144:147], v[216:219], v[44:47]
	s_setprio 0
	ds_read_b128 v[144:147], v221 offset:4096
	s_waitcnt lgkmcnt(5)
	s_setprio 1
	v_mfma_f32_16x16x32_bf16 v[48:51], v[148:151], v[204:207], v[48:51]
	v_mfma_f32_16x16x32_bf16 v[52:55], v[148:151], v[208:211], v[52:55]
	v_mfma_f32_16x16x32_bf16 v[56:59], v[148:151], v[212:215], v[56:59]
	v_mfma_f32_16x16x32_bf16 v[60:63], v[148:151], v[216:219], v[60:63]
	s_setprio 0
	ds_read_b128 v[148:151], v221 offset:6144
	s_waitcnt lgkmcnt(5)
	s_setprio 1
	v_mfma_f32_16x16x32_bf16 v[64:67], v[152:155], v[204:207], v[64:67]
	v_mfma_f32_16x16x32_bf16 v[68:71], v[152:155], v[208:211], v[68:71]
	v_mfma_f32_16x16x32_bf16 v[72:75], v[152:155], v[212:215], v[72:75]
	v_mfma_f32_16x16x32_bf16 v[76:79], v[152:155], v[216:219], v[76:79]
	s_setprio 0
	ds_read_b128 v[152:155], v221 offset:8192
	s_waitcnt lgkmcnt(5)
	s_setprio 1
	v_mfma_f32_16x16x32_bf16 v[80:83], v[156:159], v[204:207], v[80:83]
	v_mfma_f32_16x16x32_bf16 v[84:87], v[156:159], v[208:211], v[84:87]
	v_mfma_f32_16x16x32_bf16 v[88:91], v[156:159], v[212:215], v[88:91]
	v_mfma_f32_16x16x32_bf16 v[92:95], v[156:159], v[216:219], v[92:95]
	s_setprio 0
	ds_read_b128 v[156:159], v221 offset:10240
	s_waitcnt lgkmcnt(0)
	s_barrier
	v_xor_b32_e32 v222, 0x4000, v222
	v_xor_b32_e32 v223, 0x4000, v223
	s_cmp_eq_u32 s53, 15
	s_cbranch_scc1 .Lop_last
	s_setprio 1
	v_mfma_f32_16x16x32_bf16 v[0:3], v[136:139], a[0:3], v[0:3]
	s_add_u32 m0, s52, 0x0
	s_add_u32 s4, s34, 0x0
	s_addc_u32 s5, s35, 0
	global_load_lds_dwordx4 v224, s[4:5]
	v_mfma_f32_16x16x32_bf16 v[4:7], v[136:139], a[4:7], v[4:7]
	v_mfma_f32_16x16x32_bf16 v[8:11], v[136:139], a[8:11], v[8:11]
	s_add_u32 m0, s52, 0x1000
	s_add_u32 s4, s34, 0x11000
	s_addc_u32 s5, s35, 0
	global_load_lds_dwordx4 v224, s[4:5]
	v_mfma_f32_16x16x32_bf16 v[12:15], v[136:139], a[12:15], v[12:15]
	v_mfma_f32_16x16x32_bf16 v[16:19], v[140:143], a[0:3], v[16:19]
	s_add_u32 m0, s52, 0x2000
	s_add_u32 s4, s34, 0x22000
	s_addc_u32 s5, s35, 0
	global_load_lds_dwordx4 v224, s[4:5]
	v_mfma_f32_16x16x32_bf16 v[20:23], v[140:143], a[4:7], v[20:23]
	v_mfma_f32_16x16x32_bf16 v[24:27], v[140:143], a[8:11], v[24:27]
	s_add_u32 m0, s52, 0x3000
	s_add_u32 s4, s34, 0x33000
	s_addc_u32 s5, s35, 0
	global_load_lds_dwordx4 v224, s[4:5]
	v_mfma_f32_16x16x32_bf16 v[28:31], v[140:143], a[12:15], v[28:31]
	v_mfma_f32_16x16x32_bf16 v[32:35], v[144:147], a[0:3], v[32:35]
	s_add_u32 m0, s52, 0x4000
	s_add_u32 s4, s34, 0x44000
	s_addc_u32 s5, s35, 0
	global_load_lds_dwordx4 v224, s[4:5]
	v_mfma_f32_16x16x32_bf16 v[36:39], v[144:147], a[4:7], v[36:39]
	v_mfma_f32_16x16x32_bf16 v[40:43], v[144:147], a[8:11], v[40:43]
	s_add_u32 m0, s52, 0x5000
	s_add_u32 s4, s34, 0x55000
	s_addc_u32 s5, s35, 0
	global_load_lds_dwordx4 v224, s[4:5]
	v_mfma_f32_16x16x32_bf16 v[44:47], v[144:147], a[12:15], v[44:47]
	v_mfma_f32_16x16x32_bf16 v[48:51], v[148:151], a[0:3], v[48:51]
	v_mfma_f32_16x16x32_bf16 v[52:55], v[148:151], a[4:7], v[52:55]
	v_mfma_f32_16x16x32_bf16 v[56:59], v[148:151], a[8:11], v[56:59]
	v_mfma_f32_16x16x32_bf16 v[60:63], v[148:151], a[12:15], v[60:63]
	v_mfma_f32_16x16x32_bf16 v[64:67], v[152:155], a[0:3], v[64:67]
	v_mfma_f32_16x16x32_bf16 v[68:71], v[152:155], a[4:7], v[68:71]
	v_mfma_f32_16x16x32_bf16 v[72:75], v[152:155], a[8:11], v[72:75]
	v_mfma_f32_16x16x32_bf16 v[76:79], v[152:155], a[12:15], v[76:79]
	v_mfma_f32_16x16x32_bf16 v[80:83], v[156:159], a[0:3], v[80:83]
	v_mfma_f32_16x16x32_bf16 v[84:87], v[156:159], a[4:7], v[84:87]
	v_mfma_f32_16x16x32_bf16 v[88:91], v[156:159], a[8:11], v[88:91]
	v_mfma_f32_16x16x32_bf16 v[92:95], v[156:159], a[12:15], v[92:95]
	s_setprio 0
	s_add_u32 s34, s34, 0x80
	s_addc_u32 s35, s35, 0
	s_add_u32 s53, s53, 1
	s_branch .Lop_k

.Lop_nopf:
	s_setprio 1
	v_mfma_f32_16x16x32_bf16 v[0:3], v[136:139], a[0:3], v[0:3]
	v_mfma_f32_16x16x32_bf16 v[4:7], v[136:139], a[4:7], v[4:7]
	v_mfma_f32_16x16x32_bf16 v[8:11], v[136:139], a[8:11], v[8:11]
	v_mfma_f32_16x16x32_bf16 v[12:15], v[136:139], a[12:15], v[12:15]
	v_mfma_f32_16x16x32_bf16 v[16:19], v[140:143], a[0:3], v[16:19]
	v_mfma_f32_16x16x32_bf16 v[20:23], v[140:143], a[4:7], v[20:23]
	v_mfma_f32_16x16x32_bf16 v[24:27], v[140:143], a[8:11], v[24:27]
	v_mfma_f32_16x16x32_bf16 v[28:31], v[140:143], a[12:15], v[28:31]
	v_mfma_f32_16x16x32_bf16 v[32:35], v[144:147], a[0:3], v[32:35]
	v_mfma_f32_16x16x32_bf16 v[36:39], v[144:147], a[4:7], v[36:39]
	v_mfma_f32_16x16x32_bf16 v[40:43], v[144:147], a[8:11], v[40:43]
	v_mfma_f32_16x16x32_bf16 v[44:47], v[144:147], a[12:15], v[44:47]
	v_mfma_f32_16x16x32_bf16 v[48:51], v[148:151], a[0:3], v[48:51]
	v_mfma_f32_16x16x32_bf16 v[52:55], v[148:151], a[4:7], v[52:55]
	v_mfma_f32_16x16x32_bf16 v[56:59], v[148:151], a[8:11], v[56:59]
	v_mfma_f32_16x16x32_bf16 v[60:63], v[148:151], a[12:15], v[60:63]
	v_mfma_f32_16x16x32_bf16 v[64:67], v[152:155], a[0:3], v[64:67]
	v_mfma_f32_16x16x32_bf16 v[68:71], v[152:155], a[4:7], v[68:71]
	v_mfma_f32_16x16x32_bf16 v[72:75], v[152:155], a[8:11], v[72:75]
	v_mfma_f32_16x16x32_bf16 v[76:79], v[152:155], a[12:15], v[76:79]
	v_mfma_f32_16x16x32_bf16 v[80:83], v[156:159], a[0:3], v[80:83]
	v_mfma_f32_16x16x32_bf16 v[84:87], v[156:159], a[4:7], v[84:87]
	v_mfma_f32_16x16x32_bf16 v[88:91], v[156:159], a[8:11], v[88:91]
	v_mfma_f32_16x16x32_bf16 v[92:95], v[156:159], a[12:15], v[92:95]
	s_setprio 0
	s_mov_b32 s55, 0x3fd744fd
	s_add_u32 s4, s50, 0x20000
	s_addc_u32 s5, s51, 0
	global_load_dwordx2 v[136:137], v225, s[4:5]
	global_load_dwordx2 v[138:139], v225, s[4:5] offset:128
	s_add_u32 s4, s50, 0x21000
	s_addc_u32 s5, s51, 0
	global_load_dwordx2 v[140:141], v225, s[4:5]
	global_load_dwordx2 v[142:143], v225, s[4:5] offset:128
	s_add_u32 s4, s50, 0x22000
	s_addc_u32 s5, s51, 0
	global_load_dwordx2 v[144:145], v225, s[4:5]
	global_load_dwordx2 v[146:147], v225, s[4:5] offset:128
	s_add_u32 s4, s50, 0x23000
	s_addc_u32 s5, s51, 0
	global_load_dwordx2 v[148:149], v225, s[4:5]
	global_load_dwordx2 v[150:151], v225, s[4:5] offset:128
	s_add_u32 s4, s50, 0x30000
	s_addc_u32 s5, s51, 0
	global_load_dwordx2 v[152:153], v225, s[4:5]
	global_load_dwordx2 v[154:155], v225, s[4:5] offset:128
	s_add_u32 s4, s50, 0x31000
	s_addc_u32 s5, s51, 0
	global_load_dwordx2 v[156:157], v225, s[4:5]
	global_load_dwordx2 v[158:159], v225, s[4:5] offset:128
	s_add_u32 s4, s50, 0x32000
	s_addc_u32 s5, s51, 0
	global_load_dwordx2 v[160:161], v225, s[4:5]
	global_load_dwordx2 v[162:163], v225, s[4:5] offset:128
	s_add_u32 s4, s50, 0x33000
	s_addc_u32 s5, s51, 0
	global_load_dwordx2 v[164:165], v225, s[4:5]
	global_load_dwordx2 v[166:167], v225, s[4:5] offset:128
	s_add_u32 s4, s50, 0x40000
	s_addc_u32 s5, s51, 0
	global_load_dwordx2 v[204:205], v225, s[4:5]
	global_load_dwordx2 v[206:207], v225, s[4:5] offset:128
	s_add_u32 s4, s50, 0x41000
	s_addc_u32 s5, s51, 0
	global_load_dwordx2 v[208:209], v225, s[4:5]
	global_load_dwordx2 v[210:211], v225, s[4:5] offset:128
	s_add_u32 s4, s50, 0x42000
	s_addc_u32 s5, s51, 0
	global_load_dwordx2 v[212:213], v225, s[4:5]
	global_load_dwordx2 v[214:215], v225, s[4:5] offset:128
	s_add_u32 s4, s50, 0x43000
	s_addc_u32 s5, s51, 0
	global_load_dwordx2 v[216:217], v225, s[4:5]
	global_load_dwordx2 v[218:219], v225, s[4:5] offset:128
	s_nop 7
	s_nop 7
	v_mul_f32_e32 v96, s55, v96
	v_mul_f32_e32 v97, s55, v97
	v_mul_f32_e32 v98, s55, v98
	v_mul_f32_e32 v99, s55, v99
	v_fmac_f32_e32 v96, v226, v0
	v_fmac_f32_e32 v97, v227, v4
	v_fmac_f32_e32 v98, v228, v8
	v_fmac_f32_e32 v99, v229, v12
	v_mul_f32_e32 v100, s55, v100
	v_mul_f32_e32 v101, s55, v101
	v_mul_f32_e32 v102, s55, v102
	v_mul_f32_e32 v103, s55, v103
	v_fmac_f32_e32 v100, v226, v1
	v_fmac_f32_e32 v101, v227, v5
	v_fmac_f32_e32 v102, v228, v9
	v_fmac_f32_e32 v103, v229, v13
	v_mul_f32_e32 v104, s55, v104
	v_mul_f32_e32 v105, s55, v105
	v_mul_f32_e32 v106, s55, v106
	v_mul_f32_e32 v107, s55, v107
	v_fmac_f32_e32 v104, v226, v2
	v_fmac_f32_e32 v105, v227, v6
	v_fmac_f32_e32 v106, v228, v10
	v_fmac_f32_e32 v107, v229, v14
	v_mul_f32_e32 v108, s55, v108
	v_mul_f32_e32 v109, s55, v109
	v_mul_f32_e32 v110, s55, v110
	v_mul_f32_e32 v111, s55, v111
	v_fmac_f32_e32 v108, v226, v3
	v_fmac_f32_e32 v109, v227, v7
	v_fmac_f32_e32 v110, v228, v11
	v_fmac_f32_e32 v111, v229, v15
	s_add_u32 s4, s50, 0x0
	s_addc_u32 s5, s51, 0
	global_store_dwordx2 v225, v[96:97], s[4:5]
	global_store_dwordx2 v225, v[98:99], s[4:5] offset:128
	s_add_u32 s4, s50, 0x1000
	s_addc_u32 s5, s51, 0
	global_store_dwordx2 v225, v[100:101], s[4:5]
	global_store_dwordx2 v225, v[102:103], s[4:5] offset:128
	s_add_u32 s4, s50, 0x2000
	s_addc_u32 s5, s51, 0
	global_store_dwordx2 v225, v[104:105], s[4:5]
	global_store_dwordx2 v225, v[106:107], s[4:5] offset:128
	s_add_u32 s4, s50, 0x3000
	s_addc_u32 s5, s51, 0
	global_store_dwordx2 v225, v[108:109], s[4:5]
	global_store_dwordx2 v225, v[110:111], s[4:5] offset:128
	s_add_u32 s4, s50, 0x50000
	s_addc_u32 s5, s51, 0
	global_load_dwordx2 v[96:97], v225, s[4:5]
	global_load_dwordx2 v[98:99], v225, s[4:5] offset:128
	s_add_u32 s4, s50, 0x51000
	s_addc_u32 s5, s51, 0
	global_load_dwordx2 v[100:101], v225, s[4:5]
	global_load_dwordx2 v[102:103], v225, s[4:5] offset:128
	s_add_u32 s4, s50, 0x52000
	s_addc_u32 s5, s51, 0
	global_load_dwordx2 v[104:105], v225, s[4:5]
	global_load_dwordx2 v[106:107], v225, s[4:5] offset:128
	s_add_u32 s4, s50, 0x53000
	s_addc_u32 s5, s51, 0
	global_load_dwordx2 v[108:109], v225, s[4:5]
	global_load_dwordx2 v[110:111], v225, s[4:5] offset:128
	s_add_u32 s4, s58, 16
	s_lshr_b32 s4, s4, 12
	s_cmp_eq_u32 s4, s59
	s_cbranch_scc1 .Lop_g1
	s_mov_b32 s59, s4
	v_mov_b32_e32 v226, v230
	v_mov_b32_e32 v227, v231
	v_mov_b32_e32 v228, v232
	v_mov_b32_e32 v229, v233

.Lip_nob2:
	ds_read_b128 v[204:207], v222
	ds_read_b128 v[208:211], v222 offset:2048
	ds_read_b128 v[212:215], v222 offset:4096
	ds_read_b128 v[216:219], v222 offset:6144
	ds_read_b128 a[0:3], v223
	ds_read_b128 a[4:7], v223 offset:2048
	ds_read_b128 a[8:11], v223 offset:4096
	ds_read_b128 a[12:15], v223 offset:6144
	ds_read_b128 v[136:139], v220
	ds_read_b128 v[140:143], v220 offset:2048
	ds_read_b128 v[144:147], v220 offset:4096
	ds_read_b128 v[148:151], v220 offset:6144
	ds_read_b128 v[152:155], v220 offset:8192
	ds_read_b128 v[156:159], v220 offset:10240
	ds_read_b128 v[160:163], v220 offset:12288
	ds_read_b128 v[164:167], v220 offset:14336
	s_waitcnt lgkmcnt(7)
	s_setprio 1
	v_mfma_f32_16x16x32_bf16 v[0:3], v[136:139], v[204:207], v[0:3]
	v_mfma_f32_16x16x32_bf16 v[4:7], v[136:139], v[208:211], v[4:7]
	v_mfma_f32_16x16x32_bf16 v[8:11], v[136:139], v[212:215], v[8:11]
	v_mfma_f32_16x16x32_bf16 v[12:15], v[136:139], v[216:219], v[12:15]
	s_setprio 0
	ds_read_b128 v[136:139], v221
	s_waitcnt lgkmcnt(7)
	s_setprio 1
	v_mfma_f32_16x16x32_bf16 v[16:19], v[140:143], v[204:207], v[16:19]
	v_mfma_f32_16x16x32_bf16 v[20:23], v[140:143], v[208:211], v[20:23]
	v_mfma_f32_16x16x32_bf16 v[24:27], v[140:143], v[212:215], v[24:27]
	v_mfma_f32_16x16x32_bf16 v[28:31], v[140:143], v[216:219], v[28:31]
	s_setprio 0
	ds_read_b128 v[140:143], v221 offset:2048
	s_waitcnt lgkmcnt(7)
	s_setprio 1
	v_mfma_f32_16x16x32_bf16 v[32:35], v[144:147], v[204:207], v[32:35]
	v_mfma_f32_16x16x32_bf16 v[36:39], v[144:147], v[208:211], v[36:39]
	v_mfma_f32_16x16x32_bf16 v[40:43], v[144:147], v[212:215], v[40:43]
	v_mfma_f32_16x16x32_bf16 v[44:47], v[144:147], v[216:219], v[44:47]
	s_setprio 0
	ds_read_b128 v[144:147], v221 offset:4096
	s_waitcnt lgkmcnt(7)
	s_setprio 1
	v_mfma_f32_16x16x32_bf16 v[48:51], v[148:151], v[204:207], v[48:51]
	v_mfma_f32_16x16x32_bf16 v[52:55], v[148:151], v[208:211], v[52:55]
	v_mfma_f32_16x16x32_bf16 v[56:59], v[148:151], v[212:215], v[56:59]
	v_mfma_f32_16x16x32_bf16 v[60:63], v[148:151], v[216:219], v[60:63]
	s_setprio 0
	ds_read_b128 v[148:151], v221 offset:6144
	s_waitcnt lgkmcnt(7)
	s_setprio 1
	v_mfma_f32_16x16x32_bf16 v[64:67], v[152:155], v[204:207], v[64:67]
	v_mfma_f32_16x16x32_bf16 v[68:71], v[152:155], v[208:211], v[68:71]
	v_mfma_f32_16x16x32_bf16 v[72:75], v[152:155], v[212:215], v[72:75]
	v_mfma_f32_16x16x32_bf16 v[76:79], v[152:155], v[216:219], v[76:79]
	s_setprio 0
	ds_read_b128 v[152:155], v221 offset:8192
	s_waitcnt lgkmcnt(7)
	s_setprio 1
	v_mfma_f32_16x16x32_bf16 v[80:83], v[156:159], v[204:207], v[80:83]
	v_mfma_f32_16x16x32_bf16 v[84:87], v[156:159], v[208:211], v[84:87]
	v_mfma_f32_16x16x32_bf16 v[88:91], v[156:159], v[212:215], v[88:91]
	v_mfma_f32_16x16x32_bf16 v[92:95], v[156:159], v[216:219], v[92:95]
	s_setprio 0
	ds_read_b128 v[156:159], v221 offset:10240
	s_waitcnt lgkmcnt(7)
	s_setprio 1
	v_mfma_f32_16x16x32_bf16 v[96:99], v[160:163], v[204:207], v[96:99]
	v_mfma_f32_16x16x32_bf16 v[100:103], v[160:163], v[208:211], v[100:103]
	v_mfma_f32_16x16x32_bf16 v[104:107], v[160:163], v[212:215], v[104:107]
	v_mfma_f32_16x16x32_bf16 v[108:111], v[160:163], v[216:219], v[108:111]
	s_setprio 0
	ds_read_b128 v[160:163], v221 offset:12288
	s_waitcnt lgkmcnt(7)
	s_setprio 1
	v_mfma_f32_16x16x32_bf16 v[112:115], v[164:167], v[204:207], v[112:115]
	v_mfma_f32_16x16x32_bf16 v[116:119], v[164:167], v[208:211], v[116:119]
	v_mfma_f32_16x16x32_bf16 v[120:123], v[164:167], v[212:215], v[120:123]
	v_mfma_f32_16x16x32_bf16 v[124:127], v[164:167], v[216:219], v[124:127]
	s_setprio 0
	ds_read_b128 v[164:167], v221 offset:14336
	s_waitcnt lgkmcnt(0)
	s_barrier
	v_xor_b32_e32 v222, 0x4000, v222
	v_xor_b32_e32 v223, 0x4000, v223
	s_cmp_eq_u32 s53, 15
	s_cbranch_scc1 .Lip_last
	s_setprio 1
	v_mfma_f32_16x16x32_bf16 v[0:3], v[136:139], a[0:3], v[0:3]
	s_add_u32 m0, s52, 0x0
	s_add_u32 s4, s34, 0x0
	s_addc_u32 s5, s35, 0
	global_load_lds_dwordx4 v224, s[4:5]
	v_mfma_f32_16x16x32_bf16 v[4:7], v[136:139], a[4:7], v[4:7]
	v_mfma_f32_16x16x32_bf16 v[8:11], v[136:139], a[8:11], v[8:11]
	s_add_u32 m0, s52, 0x1000
	s_add_u32 s4, s34, 0x11000
	s_addc_u32 s5, s35, 0
	global_load_lds_dwordx4 v224, s[4:5]
	v_mfma_f32_16x16x32_bf16 v[12:15], v[136:139], a[12:15], v[12:15]
	v_mfma_f32_16x16x32_bf16 v[16:19], v[140:143], a[0:3], v[16:19]
	s_add_u32 m0, s52, 0x2000
	s_add_u32 s4, s34, 0x22000
	s_addc_u32 s5, s35, 0
	global_load_lds_dwordx4 v224, s[4:5]
	v_mfma_f32_16x16x32_bf16 v[20:23], v[140:143], a[4:7], v[20:23]
	v_mfma_f32_16x16x32_bf16 v[24:27], v[140:143], a[8:11], v[24:27]
	s_add_u32 m0, s52, 0x3000
	s_add_u32 s4, s34, 0x33000
	s_addc_u32 s5, s35, 0
	global_load_lds_dwordx4 v224, s[4:5]
	v_mfma_f32_16x16x32_bf16 v[28:31], v[140:143], a[12:15], v[28:31]
	v_mfma_f32_16x16x32_bf16 v[32:35], v[144:147], a[0:3], v[32:35]
	s_add_u32 m0, s52, 0x4000
	s_add_u32 s4, s34, 0x44000
	s_addc_u32 s5, s35, 0
	global_load_lds_dwordx4 v224, s[4:5]
	v_mfma_f32_16x16x32_bf16 v[36:39], v[144:147], a[4:7], v[36:39]
	v_mfma_f32_16x16x32_bf16 v[40:43], v[144:147], a[8:11], v[40:43]
	s_add_u32 m0, s52, 0x5000
	s_add_u32 s4, s34, 0x55000
	s_addc_u32 s5, s35, 0
	global_load_lds_dwordx4 v224, s[4:5]
	v_mfma_f32_16x16x32_bf16 v[44:47], v[144:147], a[12:15], v[44:47]
	v_mfma_f32_16x16x32_bf16 v[48:51], v[148:151], a[0:3], v[48:51]
	s_add_u32 m0, s52, 0x6000
	s_add_u32 s4, s34, 0x66000
	s_addc_u32 s5, s35, 0
	global_load_lds_dwordx4 v224, s[4:5]
	v_mfma_f32_16x16x32_bf16 v[52:55], v[148:151], a[4:7], v[52:55]
	v_mfma_f32_16x16x32_bf16 v[56:59], v[148:151], a[8:11], v[56:59]
	s_add_u32 m0, s52, 0x7000
	s_add_u32 s4, s34, 0x77000
	s_addc_u32 s5, s35, 0
	global_load_lds_dwordx4 v224, s[4:5]
	v_mfma_f32_16x16x32_bf16 v[60:63], v[148:151], a[12:15], v[60:63]
	v_mfma_f32_16x16x32_bf16 v[64:67], v[152:155], a[0:3], v[64:67]
	v_mfma_f32_16x16x32_bf16 v[68:71], v[152:155], a[4:7], v[68:71]
	v_mfma_f32_16x16x32_bf16 v[72:75], v[152:155], a[8:11], v[72:75]
	v_mfma_f32_16x16x32_bf16 v[76:79], v[152:155], a[12:15], v[76:79]
	v_mfma_f32_16x16x32_bf16 v[80:83], v[156:159], a[0:3], v[80:83]
	v_mfma_f32_16x16x32_bf16 v[84:87], v[156:159], a[4:7], v[84:87]
	v_mfma_f32_16x16x32_bf16 v[88:91], v[156:159], a[8:11], v[88:91]
	v_mfma_f32_16x16x32_bf16 v[92:95], v[156:159], a[12:15], v[92:95]
	v_mfma_f32_16x16x32_bf16 v[96:99], v[160:163], a[0:3], v[96:99]
	v_mfma_f32_16x16x32_bf16 v[100:103], v[160:163], a[4:7], v[100:103]
	v_mfma_f32_16x16x32_bf16 v[104:107], v[160:163], a[8:11], v[104:107]
	v_mfma_f32_16x16x32_bf16 v[108:111], v[160:163], a[12:15], v[108:111]
	v_mfma_f32_16x16x32_bf16 v[112:115], v[164:167], a[0:3], v[112:115]
	v_mfma_f32_16x16x32_bf16 v[116:119], v[164:167], a[4:7], v[116:119]
	v_mfma_f32_16x16x32_bf16 v[120:123], v[164:167], a[8:11], v[120:123]
	v_mfma_f32_16x16x32_bf16 v[124:127], v[164:167], a[12:15], v[124:127]
	s_setprio 0
	s_add_u32 s34, s34, 0x80
	s_addc_u32 s35, s35, 0
	s_add_u32 s53, s53, 1
	s_branch .Lip_k

.Lip_nopf:
	s_setprio 1
	v_mfma_f32_16x16x32_bf16 v[0:3], v[136:139], a[0:3], v[0:3]
	v_mfma_f32_16x16x32_bf16 v[4:7], v[136:139], a[4:7], v[4:7]
	v_mfma_f32_16x16x32_bf16 v[8:11], v[136:139], a[8:11], v[8:11]
	v_mfma_f32_16x16x32_bf16 v[12:15], v[136:139], a[12:15], v[12:15]
	v_mfma_f32_16x16x32_bf16 v[16:19], v[140:143], a[0:3], v[16:19]
	v_mfma_f32_16x16x32_bf16 v[20:23], v[140:143], a[4:7], v[20:23]
	v_mfma_f32_16x16x32_bf16 v[24:27], v[140:143], a[8:11], v[24:27]
	v_mfma_f32_16x16x32_bf16 v[28:31], v[140:143], a[12:15], v[28:31]
	v_mfma_f32_16x16x32_bf16 v[32:35], v[144:147], a[0:3], v[32:35]
	v_mfma_f32_16x16x32_bf16 v[36:39], v[144:147], a[4:7], v[36:39]
	v_mfma_f32_16x16x32_bf16 v[40:43], v[144:147], a[8:11], v[40:43]
	v_mfma_f32_16x16x32_bf16 v[44:47], v[144:147], a[12:15], v[44:47]
	v_mfma_f32_16x16x32_bf16 v[48:51], v[148:151], a[0:3], v[48:51]
	v_mfma_f32_16x16x32_bf16 v[52:55], v[148:151], a[4:7], v[52:55]
	v_mfma_f32_16x16x32_bf16 v[56:59], v[148:151], a[8:11], v[56:59]
	v_mfma_f32_16x16x32_bf16 v[60:63], v[148:151], a[12:15], v[60:63]
	v_mfma_f32_16x16x32_bf16 v[64:67], v[152:155], a[0:3], v[64:67]
	v_mfma_f32_16x16x32_bf16 v[68:71], v[152:155], a[4:7], v[68:71]
	v_mfma_f32_16x16x32_bf16 v[72:75], v[152:155], a[8:11], v[72:75]
	v_mfma_f32_16x16x32_bf16 v[76:79], v[152:155], a[12:15], v[76:79]
	v_mfma_f32_16x16x32_bf16 v[80:83], v[156:159], a[0:3], v[80:83]
	v_mfma_f32_16x16x32_bf16 v[84:87], v[156:159], a[4:7], v[84:87]
	v_mfma_f32_16x16x32_bf16 v[88:91], v[156:159], a[8:11], v[88:91]
	v_mfma_f32_16x16x32_bf16 v[92:95], v[156:159], a[12:15], v[92:95]
	v_mfma_f32_16x16x32_bf16 v[96:99], v[160:163], a[0:3], v[96:99]
	v_mfma_f32_16x16x32_bf16 v[100:103], v[160:163], a[4:7], v[100:103]
	v_mfma_f32_16x16x32_bf16 v[104:107], v[160:163], a[8:11], v[104:107]
	v_mfma_f32_16x16x32_bf16 v[108:111], v[160:163], a[12:15], v[108:111]
	v_mfma_f32_16x16x32_bf16 v[112:115], v[164:167], a[0:3], v[112:115]
	v_mfma_f32_16x16x32_bf16 v[116:119], v[164:167], a[4:7], v[116:119]
	v_mfma_f32_16x16x32_bf16 v[120:123], v[164:167], a[8:11], v[120:123]
	v_mfma_f32_16x16x32_bf16 v[124:127], v[164:167], a[12:15], v[124:127]
	s_setprio 0
	s_nop 7
	s_nop 7
	s_and_b32 s55, s56, 0xff
	s_lshr_b32 s53, s56, 8
	v_readlane_b32 s4, v235, 34
	v_readlane_b32 s5, v235, 35
	s_mul_i32 s46, s53, 0x360000
	s_lshl_b32 s50, s55, 9
	s_add_u32 s46, s46, s50
	s_add_u32 s46, s46, 0xfae6000
	s_add_u32 s46, s46, s4
	s_addc_u32 s47, s5, 0
	s_mul_i32 s50, s53, 0x30000
	s_lshl_b32 s51, s55, 8
	s_add_u32 s50, s50, s51
	s_add_u32 s50, s50, 0x19ce5a00
	s_add_u32 s50, s50, s4
	s_addc_u32 s51, s5, 0
	v_mov_b32_e32 v226, s46
	v_mov_b32_e32 v227, s47
	v_add_co_u32_e32 v226, vcc, v226, v225
	s_nop 1
	v_addc_co_u32_e32 v227, vcc, 0, v227, vcc
	v_mov_b32_e32 v228, v0
	v_mov_b32_e32 v229, v4
	v_mov_b32_e32 v230, v8
	v_mov_b32_e32 v231, v12
	global_store_dwordx2 v[226:227], v[228:229], off
	global_store_dwordx2 v[226:227], v[230:231], off offset:128
	s_mov_b64 s[4:5], 0x3600
	v_lshl_add_u64 v[226:227], v[226:227], 0, s[4:5]
	v_mov_b32_e32 v228, v1
	v_mov_b32_e32 v229, v5
	v_mov_b32_e32 v230, v9
	v_mov_b32_e32 v231, v13
	global_store_dwordx2 v[226:227], v[228:229], off
	global_store_dwordx2 v[226:227], v[230:231], off offset:128
	s_mov_b64 s[4:5], 0x3600
	v_lshl_add_u64 v[226:227], v[226:227], 0, s[4:5]
	v_mov_b32_e32 v228, v2
	v_mov_b32_e32 v229, v6
	v_mov_b32_e32 v230, v10
	v_mov_b32_e32 v231, v14
	global_store_dwordx2 v[226:227], v[228:229], off
	global_store_dwordx2 v[226:227], v[230:231], off offset:128
	s_mov_b64 s[4:5], 0x3600
	v_lshl_add_u64 v[226:227], v[226:227], 0, s[4:5]
	v_mov_b32_e32 v228, v3
	v_mov_b32_e32 v229, v7
	v_mov_b32_e32 v230, v11
	v_mov_b32_e32 v231, v15
	global_store_dwordx2 v[226:227], v[228:229], off
	global_store_dwordx2 v[226:227], v[230:231], off offset:128
	s_mov_b64 s[4:5], 0x2be00
	v_lshl_add_u64 v[226:227], v[226:227], 0, s[4:5]
	v_mov_b32_e32 v228, v16
	v_mov_b32_e32 v229, v20
	v_mov_b32_e32 v230, v24
	v_mov_b32_e32 v231, v28
	global_store_dwordx2 v[226:227], v[228:229], off
	global_store_dwordx2 v[226:227], v[230:231], off offset:128
	s_mov_b64 s[4:5], 0x3600
	v_lshl_add_u64 v[226:227], v[226:227], 0, s[4:5]
	v_mov_b32_e32 v228, v17
	v_mov_b32_e32 v229, v21
	v_mov_b32_e32 v230, v25
	v_mov_b32_e32 v231, v29
	global_store_dwordx2 v[226:227], v[228:229], off
	global_store_dwordx2 v[226:227], v[230:231], off offset:128
	s_mov_b64 s[4:5], 0x3600
	v_lshl_add_u64 v[226:227], v[226:227], 0, s[4:5]
	v_mov_b32_e32 v228, v18
	v_mov_b32_e32 v229, v22
	v_mov_b32_e32 v230, v26
	v_mov_b32_e32 v231, v30
	global_store_dwordx2 v[226:227], v[228:229], off
	global_store_dwordx2 v[226:227], v[230:231], off offset:128
	s_mov_b64 s[4:5], 0x3600
	v_lshl_add_u64 v[226:227], v[226:227], 0, s[4:5]
	v_mov_b32_e32 v228, v19
	v_mov_b32_e32 v229, v23
	v_mov_b32_e32 v230, v27
	v_mov_b32_e32 v231, v31
	global_store_dwordx2 v[226:227], v[228:229], off
	global_store_dwordx2 v[226:227], v[230:231], off offset:128
	s_mov_b64 s[4:5], 0x2be00
	v_lshl_add_u64 v[226:227], v[226:227], 0, s[4:5]
	v_mov_b32_e32 v228, v32
	v_mov_b32_e32 v229, v36
	v_mov_b32_e32 v230, v40
	v_mov_b32_e32 v231, v44
	global_store_dwordx2 v[226:227], v[228:229], off
	global_store_dwordx2 v[226:227], v[230:231], off offset:128
	s_mov_b64 s[4:5], 0x3600
	v_lshl_add_u64 v[226:227], v[226:227], 0, s[4:5]
	v_mov_b32_e32 v228, v33
	v_mov_b32_e32 v229, v37
	v_mov_b32_e32 v230, v41
	v_mov_b32_e32 v231, v45
	global_store_dwordx2 v[226:227], v[228:229], off
	global_store_dwordx2 v[226:227], v[230:231], off offset:128
	s_mov_b64 s[4:5], 0x3600
	v_lshl_add_u64 v[226:227], v[226:227], 0, s[4:5]
	v_mov_b32_e32 v228, v34
	v_mov_b32_e32 v229, v38
	v_mov_b32_e32 v230, v42
	v_mov_b32_e32 v231, v46
	global_store_dwordx2 v[226:227], v[228:229], off
	global_store_dwordx2 v[226:227], v[230:231], off offset:128
	s_mov_b64 s[4:5], 0x3600
	v_lshl_add_u64 v[226:227], v[226:227], 0, s[4:5]
	v_mov_b32_e32 v228, v35
	v_mov_b32_e32 v229, v39
	v_mov_b32_e32 v230, v43
	v_mov_b32_e32 v231, v47
	global_store_dwordx2 v[226:227], v[228:229], off
	global_store_dwordx2 v[226:227], v[230:231], off offset:128
	s_mov_b64 s[4:5], 0x2be00
	v_lshl_add_u64 v[226:227], v[226:227], 0, s[4:5]
	v_mov_b32_e32 v228, v48
	v_mov_b32_e32 v229, v52
	v_mov_b32_e32 v230, v56
	v_mov_b32_e32 v231, v60
	global_store_dwordx2 v[226:227], v[228:229], off
	global_store_dwordx2 v[226:227], v[230:231], off offset:128
	s_mov_b64 s[4:5], 0x3600
	v_lshl_add_u64 v[226:227], v[226:227], 0, s[4:5]
	v_mov_b32_e32 v228, v49
	v_mov_b32_e32 v229, v53
	v_mov_b32_e32 v230, v57
	v_mov_b32_e32 v231, v61
	global_store_dwordx2 v[226:227], v[228:229], off
	global_store_dwordx2 v[226:227], v[230:231], off offset:128
	s_mov_b64 s[4:5], 0x3600
	v_lshl_add_u64 v[226:227], v[226:227], 0, s[4:5]
	v_mov_b32_e32 v228, v50
	v_mov_b32_e32 v229, v54
	v_mov_b32_e32 v230, v58
	v_mov_b32_e32 v231, v62
	global_store_dwordx2 v[226:227], v[228:229], off
	global_store_dwordx2 v[226:227], v[230:231], off offset:128
	s_mov_b64 s[4:5], 0x3600
	v_lshl_add_u64 v[226:227], v[226:227], 0, s[4:5]
	v_mov_b32_e32 v228, v51
	v_mov_b32_e32 v229, v55
	v_mov_b32_e32 v230, v59
	v_mov_b32_e32 v231, v63
	global_store_dwordx2 v[226:227], v[228:229], off
	global_store_dwordx2 v[226:227], v[230:231], off offset:128
	s_mov_b64 s[4:5], 0x2be00
	v_lshl_add_u64 v[226:227], v[226:227], 0, s[4:5]
	v_mov_b32_e32 v228, v64
	v_mov_b32_e32 v229, v68
	v_mov_b32_e32 v230, v72
	v_mov_b32_e32 v231, v76
	global_store_dwordx2 v[226:227], v[228:229], off
	global_store_dwordx2 v[226:227], v[230:231], off offset:128
	s_mov_b64 s[4:5], 0x3600
	v_lshl_add_u64 v[226:227], v[226:227], 0, s[4:5]
	v_mov_b32_e32 v228, v65
	v_mov_b32_e32 v229, v69
	v_mov_b32_e32 v230, v73
	v_mov_b32_e32 v231, v77
	global_store_dwordx2 v[226:227], v[228:229], off
	global_store_dwordx2 v[226:227], v[230:231], off offset:128
	s_mov_b64 s[4:5], 0x3600
	v_lshl_add_u64 v[226:227], v[226:227], 0, s[4:5]
	v_mov_b32_e32 v228, v66
	v_mov_b32_e32 v229, v70
	v_mov_b32_e32 v230, v74
	v_mov_b32_e32 v231, v78
	global_store_dwordx2 v[226:227], v[228:229], off
	global_store_dwordx2 v[226:227], v[230:231], off offset:128
	s_mov_b64 s[4:5], 0x3600
	v_lshl_add_u64 v[226:227], v[226:227], 0, s[4:5]
	v_mov_b32_e32 v228, v67
	v_mov_b32_e32 v229, v71
	v_mov_b32_e32 v230, v75
	v_mov_b32_e32 v231, v79
	global_store_dwordx2 v[226:227], v[228:229], off
	global_store_dwordx2 v[226:227], v[230:231], off offset:128
	s_mov_b64 s[4:5], 0x2be00
	v_lshl_add_u64 v[226:227], v[226:227], 0, s[4:5]
	v_mov_b32_e32 v228, v80
	v_mov_b32_e32 v229, v84
	v_mov_b32_e32 v230, v88
	v_mov_b32_e32 v231, v92
	global_store_dwordx2 v[226:227], v[228:229], off
	global_store_dwordx2 v[226:227], v[230:231], off offset:128
	s_mov_b64 s[4:5], 0x3600
	v_lshl_add_u64 v[226:227], v[226:227], 0, s[4:5]
	v_mov_b32_e32 v228, v81
	v_mov_b32_e32 v229, v85
	v_mov_b32_e32 v230, v89
	v_mov_b32_e32 v231, v93
	global_store_dwordx2 v[226:227], v[228:229], off
	global_store_dwordx2 v[226:227], v[230:231], off offset:128
	s_mov_b64 s[4:5], 0x3600
	v_lshl_add_u64 v[226:227], v[226:227], 0, s[4:5]
	v_mov_b32_e32 v228, v82
	v_mov_b32_e32 v229, v86
	v_mov_b32_e32 v230, v90
	v_mov_b32_e32 v231, v94
	global_store_dwordx2 v[226:227], v[228:229], off
	global_store_dwordx2 v[226:227], v[230:231], off offset:128
	s_mov_b64 s[4:5], 0x3600
	v_lshl_add_u64 v[226:227], v[226:227], 0, s[4:5]
	v_mov_b32_e32 v228, v83
	v_mov_b32_e32 v229, v87
	v_mov_b32_e32 v230, v91
	v_mov_b32_e32 v231, v95
	global_store_dwordx2 v[226:227], v[228:229], off
	global_store_dwordx2 v[226:227], v[230:231], off offset:128
	s_mov_b64 s[4:5], 0x2be00
	v_lshl_add_u64 v[226:227], v[226:227], 0, s[4:5]
	v_mov_b32_e32 v228, v96
	v_mov_b32_e32 v229, v100
	v_mov_b32_e32 v230, v104
	v_mov_b32_e32 v231, v108
	global_store_dwordx2 v[226:227], v[228:229], off
	global_store_dwordx2 v[226:227], v[230:231], off offset:128
	s_mov_b64 s[4:5], 0x3600
	v_lshl_add_u64 v[226:227], v[226:227], 0, s[4:5]
	v_mov_b32_e32 v228, v97
	v_mov_b32_e32 v229, v101
	v_mov_b32_e32 v230, v105
	v_mov_b32_e32 v231, v109
	global_store_dwordx2 v[226:227], v[228:229], off
	global_store_dwordx2 v[226:227], v[230:231], off offset:128
	s_mov_b64 s[4:5], 0x3600
	v_lshl_add_u64 v[226:227], v[226:227], 0, s[4:5]
	v_mov_b32_e32 v228, v98
	v_mov_b32_e32 v229, v102
	v_mov_b32_e32 v230, v106
	v_mov_b32_e32 v231, v110
	global_store_dwordx2 v[226:227], v[228:229], off
	global_store_dwordx2 v[226:227], v[230:231], off offset:128
	s_mov_b64 s[4:5], 0x3600
	v_lshl_add_u64 v[226:227], v[226:227], 0, s[4:5]
	v_mov_b32_e32 v228, v99
	v_mov_b32_e32 v229, v103
	v_mov_b32_e32 v230, v107
	v_mov_b32_e32 v231, v111
	global_store_dwordx2 v[226:227], v[228:229], off
	global_store_dwordx2 v[226:227], v[230:231], off offset:128
	s_mov_b64 s[4:5], 0x2be00
	v_lshl_add_u64 v[226:227], v[226:227], 0, s[4:5]
	v_mov_b32_e32 v228, v112
	v_mov_b32_e32 v229, v116
	v_mov_b32_e32 v230, v120
	v_mov_b32_e32 v231, v124
	global_store_dwordx2 v[226:227], v[228:229], off
	global_store_dwordx2 v[226:227], v[230:231], off offset:128
	s_mov_b64 s[4:5], 0x3600
	v_lshl_add_u64 v[226:227], v[226:227], 0, s[4:5]
	v_mov_b32_e32 v228, v113
	v_mov_b32_e32 v229, v117
	v_mov_b32_e32 v230, v121
	v_mov_b32_e32 v231, v125
	global_store_dwordx2 v[226:227], v[228:229], off
	global_store_dwordx2 v[226:227], v[230:231], off offset:128
	s_mov_b64 s[4:5], 0x3600
	v_lshl_add_u64 v[226:227], v[226:227], 0, s[4:5]
	v_mov_b32_e32 v228, v114
	v_mov_b32_e32 v229, v118
	v_mov_b32_e32 v230, v122
	v_mov_b32_e32 v231, v126
	global_store_dwordx2 v[226:227], v[228:229], off
	global_store_dwordx2 v[226:227], v[230:231], off offset:128
	s_mov_b64 s[4:5], 0x3600
	v_lshl_add_u64 v[226:227], v[226:227], 0, s[4:5]
	v_mov_b32_e32 v228, v115
	v_mov_b32_e32 v229, v119
	v_mov_b32_e32 v230, v123
	v_mov_b32_e32 v231, v127
	global_store_dwordx2 v[226:227], v[228:229], off
	global_store_dwordx2 v[226:227], v[230:231], off offset:128
	s_and_b32 s55, s56, 0xff
	s_sub_u32 s55, s55, 6
	s_cmp_gt_u32 s55, 2
	s_cbranch_scc1 .Lip_nolin

.Lfo_nob:
	ds_read_b128 v[204:207], v222
	ds_read_b128 v[208:211], v222 offset:2048
	ds_read_b128 v[212:215], v222 offset:4096
	ds_read_b128 v[216:219], v222 offset:6144
	ds_read_b128 a[0:3], v223
	ds_read_b128 a[4:7], v223 offset:2048
	ds_read_b128 a[8:11], v223 offset:4096
	ds_read_b128 a[12:15], v223 offset:6144
	ds_read_b128 v[136:139], v220
	ds_read_b128 v[140:143], v220 offset:2048
	ds_read_b128 v[144:147], v220 offset:4096
	ds_read_b128 v[148:151], v220 offset:6144
	ds_read_b128 v[152:155], v220 offset:8192
	ds_read_b128 v[156:159], v220 offset:10240
	s_waitcnt lgkmcnt(5)
	s_setprio 1
	v_mfma_f32_16x16x32_bf16 v[0:3], v[136:139], v[204:207], v[0:3]
	v_mfma_f32_16x16x32_bf16 v[4:7], v[136:139], v[208:211], v[4:7]
	v_mfma_f32_16x16x32_bf16 v[8:11], v[136:139], v[212:215], v[8:11]
	v_mfma_f32_16x16x32_bf16 v[12:15], v[136:139], v[216:219], v[12:15]
	s_setprio 0
	ds_read_b128 v[136:139], v221
	s_waitcnt lgkmcnt(5)
	s_setprio 1
	v_mfma_f32_16x16x32_bf16 v[16:19], v[140:143], v[204:207], v[16:19]
	v_mfma_f32_16x16x32_bf16 v[20:23], v[140:143], v[208:211], v[20:23]
	v_mfma_f32_16x16x32_bf16 v[24:27], v[140:143], v[212:215], v[24:27]
	v_mfma_f32_16x16x32_bf16 v[28:31], v[140:143], v[216:219], v[28:31]
	s_setprio 0
	ds_read_b128 v[140:143], v221 offset:2048
	s_waitcnt lgkmcnt(5)
	s_setprio 1
	v_mfma_f32_16x16x32_bf16 v[32:35], v[144:147], v[204:207], v[32:35]
	v_mfma_f32_16x16x32_bf16 v[36:39], v[144:147], v[208:211], v[36:39]
	v_mfma_f32_16x16x32_bf16 v[40:43], v[144:147], v[212:215], v[40:43]
	v_mfma_f32_16x16x32_bf16 v[44:47], v[144:147], v[216:219], v[44:47]
	s_setprio 0
	ds_read_b128 v[144:147], v221 offset:4096
	s_waitcnt lgkmcnt(5)
	s_setprio 1
	v_mfma_f32_16x16x32_bf16 v[48:51], v[148:151], v[204:207], v[48:51]
	v_mfma_f32_16x16x32_bf16 v[52:55], v[148:151], v[208:211], v[52:55]
	v_mfma_f32_16x16x32_bf16 v[56:59], v[148:151], v[212:215], v[56:59]
	v_mfma_f32_16x16x32_bf16 v[60:63], v[148:151], v[216:219], v[60:63]
	s_setprio 0
	ds_read_b128 v[148:151], v221 offset:6144
	s_waitcnt lgkmcnt(5)
	s_setprio 1
	v_mfma_f32_16x16x32_bf16 v[64:67], v[152:155], v[204:207], v[64:67]
	v_mfma_f32_16x16x32_bf16 v[68:71], v[152:155], v[208:211], v[68:71]
	v_mfma_f32_16x16x32_bf16 v[72:75], v[152:155], v[212:215], v[72:75]
	v_mfma_f32_16x16x32_bf16 v[76:79], v[152:155], v[216:219], v[76:79]
	s_setprio 0
	ds_read_b128 v[152:155], v221 offset:8192
	s_waitcnt lgkmcnt(5)
	s_setprio 1
	v_mfma_f32_16x16x32_bf16 v[80:83], v[156:159], v[204:207], v[80:83]
	v_mfma_f32_16x16x32_bf16 v[84:87], v[156:159], v[208:211], v[84:87]
	v_mfma_f32_16x16x32_bf16 v[88:91], v[156:159], v[212:215], v[88:91]
	v_mfma_f32_16x16x32_bf16 v[92:95], v[156:159], v[216:219], v[92:95]
	s_setprio 0
	ds_read_b128 v[156:159], v221 offset:10240
	s_waitcnt lgkmcnt(0)
	s_barrier
	v_xor_b32_e32 v222, 0x4000, v222
	v_xor_b32_e32 v223, 0x4000, v223
	s_cmp_eq_u32 s53, 43
	s_cbranch_scc1 .Lfo_last
	s_setprio 1
	v_mfma_f32_16x16x32_bf16 v[0:3], v[136:139], a[0:3], v[0:3]
	s_add_u32 m0, s52, 0x0
	s_add_u32 s4, s34, 0x0
	s_addc_u32 s5, s35, 0
	global_load_lds_dwordx4 v224, s[4:5]
	v_mfma_f32_16x16x32_bf16 v[4:7], v[136:139], a[4:7], v[4:7]
	v_mfma_f32_16x16x32_bf16 v[8:11], v[136:139], a[8:11], v[8:11]
	s_add_u32 m0, s52, 0x1000
	s_add_u32 s4, s34, 0x2d000
	s_addc_u32 s5, s35, 0
	global_load_lds_dwordx4 v224, s[4:5]
	v_mfma_f32_16x16x32_bf16 v[12:15], v[136:139], a[12:15], v[12:15]
	v_mfma_f32_16x16x32_bf16 v[16:19], v[140:143], a[0:3], v[16:19]
	s_add_u32 m0, s52, 0x2000
	s_add_u32 s4, s34, 0x5a000
	s_addc_u32 s5, s35, 0
	global_load_lds_dwordx4 v224, s[4:5]
	v_mfma_f32_16x16x32_bf16 v[20:23], v[140:143], a[4:7], v[20:23]
	v_mfma_f32_16x16x32_bf16 v[24:27], v[140:143], a[8:11], v[24:27]
	s_add_u32 m0, s52, 0x3000
	s_add_u32 s4, s34, 0x87000
	s_addc_u32 s5, s35, 0
	global_load_lds_dwordx4 v224, s[4:5]
	v_mfma_f32_16x16x32_bf16 v[28:31], v[140:143], a[12:15], v[28:31]
	v_mfma_f32_16x16x32_bf16 v[32:35], v[144:147], a[0:3], v[32:35]
	s_add_u32 m0, s52, 0x4000
	s_add_u32 s4, s34, 0xb4000
	s_addc_u32 s5, s35, 0
	global_load_lds_dwordx4 v224, s[4:5]
	v_mfma_f32_16x16x32_bf16 v[36:39], v[144:147], a[4:7], v[36:39]
	v_mfma_f32_16x16x32_bf16 v[40:43], v[144:147], a[8:11], v[40:43]
	s_add_u32 m0, s52, 0x5000
	s_add_u32 s4, s34, 0xe1000
	s_addc_u32 s5, s35, 0
	global_load_lds_dwordx4 v224, s[4:5]
	v_mfma_f32_16x16x32_bf16 v[44:47], v[144:147], a[12:15], v[44:47]
	v_mfma_f32_16x16x32_bf16 v[48:51], v[148:151], a[0:3], v[48:51]
	v_mfma_f32_16x16x32_bf16 v[52:55], v[148:151], a[4:7], v[52:55]
	v_mfma_f32_16x16x32_bf16 v[56:59], v[148:151], a[8:11], v[56:59]
	v_mfma_f32_16x16x32_bf16 v[60:63], v[148:151], a[12:15], v[60:63]
	v_mfma_f32_16x16x32_bf16 v[64:67], v[152:155], a[0:3], v[64:67]
	v_mfma_f32_16x16x32_bf16 v[68:71], v[152:155], a[4:7], v[68:71]
	v_mfma_f32_16x16x32_bf16 v[72:75], v[152:155], a[8:11], v[72:75]
	v_mfma_f32_16x16x32_bf16 v[76:79], v[152:155], a[12:15], v[76:79]
	v_mfma_f32_16x16x32_bf16 v[80:83], v[156:159], a[0:3], v[80:83]
	v_mfma_f32_16x16x32_bf16 v[84:87], v[156:159], a[4:7], v[84:87]
	v_mfma_f32_16x16x32_bf16 v[88:91], v[156:159], a[8:11], v[88:91]
	v_mfma_f32_16x16x32_bf16 v[92:95], v[156:159], a[12:15], v[92:95]
	s_setprio 0
	s_add_u32 s34, s34, 0x80
	s_addc_u32 s35, s35, 0
	s_add_u32 s53, s53, 1
	s_branch .Lfo_k

.Lfo_nopf:
	s_setprio 1
	v_mfma_f32_16x16x32_bf16 v[0:3], v[136:139], a[0:3], v[0:3]
	v_mfma_f32_16x16x32_bf16 v[4:7], v[136:139], a[4:7], v[4:7]
	v_mfma_f32_16x16x32_bf16 v[8:11], v[136:139], a[8:11], v[8:11]
	v_mfma_f32_16x16x32_bf16 v[12:15], v[136:139], a[12:15], v[12:15]
	v_mfma_f32_16x16x32_bf16 v[16:19], v[140:143], a[0:3], v[16:19]
	v_mfma_f32_16x16x32_bf16 v[20:23], v[140:143], a[4:7], v[20:23]
	v_mfma_f32_16x16x32_bf16 v[24:27], v[140:143], a[8:11], v[24:27]
	v_mfma_f32_16x16x32_bf16 v[28:31], v[140:143], a[12:15], v[28:31]
	v_mfma_f32_16x16x32_bf16 v[32:35], v[144:147], a[0:3], v[32:35]
	v_mfma_f32_16x16x32_bf16 v[36:39], v[144:147], a[4:7], v[36:39]
	v_mfma_f32_16x16x32_bf16 v[40:43], v[144:147], a[8:11], v[40:43]
	v_mfma_f32_16x16x32_bf16 v[44:47], v[144:147], a[12:15], v[44:47]
	v_mfma_f32_16x16x32_bf16 v[48:51], v[148:151], a[0:3], v[48:51]
	v_mfma_f32_16x16x32_bf16 v[52:55], v[148:151], a[4:7], v[52:55]
	v_mfma_f32_16x16x32_bf16 v[56:59], v[148:151], a[8:11], v[56:59]
	v_mfma_f32_16x16x32_bf16 v[60:63], v[148:151], a[12:15], v[60:63]
	v_mfma_f32_16x16x32_bf16 v[64:67], v[152:155], a[0:3], v[64:67]
	v_mfma_f32_16x16x32_bf16 v[68:71], v[152:155], a[4:7], v[68:71]
	v_mfma_f32_16x16x32_bf16 v[72:75], v[152:155], a[8:11], v[72:75]
	v_mfma_f32_16x16x32_bf16 v[76:79], v[152:155], a[12:15], v[76:79]
	v_mfma_f32_16x16x32_bf16 v[80:83], v[156:159], a[0:3], v[80:83]
	v_mfma_f32_16x16x32_bf16 v[84:87], v[156:159], a[4:7], v[84:87]
	v_mfma_f32_16x16x32_bf16 v[88:91], v[156:159], a[8:11], v[88:91]
	v_mfma_f32_16x16x32_bf16 v[92:95], v[156:159], a[12:15], v[92:95]
	s_setprio 0
	s_mov_b32 s55, 0x3fd744fd
	v_mul_f32_e32 v226, 0.5, v226
	v_mul_f32_e32 v227, 0.5, v227
	v_mul_f32_e32 v228, 0.5, v228
	v_mul_f32_e32 v229, 0.5, v229
	v_mul_f32_e32 v230, 0.5, v230
	v_mul_f32_e32 v231, 0.5, v231
	v_mul_f32_e32 v232, 0.5, v232
	v_mul_f32_e32 v233, 0.5, v233
	s_add_u32 s4, s50, 0x20000
	s_addc_u32 s5, s51, 0
	global_load_dwordx2 v[136:137], v225, s[4:5]
	global_load_dwordx2 v[138:139], v225, s[4:5] offset:128
	s_add_u32 s4, s50, 0x21000
	s_addc_u32 s5, s51, 0
	global_load_dwordx2 v[140:141], v225, s[4:5]
	global_load_dwordx2 v[142:143], v225, s[4:5] offset:128
	s_add_u32 s4, s50, 0x22000
	s_addc_u32 s5, s51, 0
	global_load_dwordx2 v[144:145], v225, s[4:5]
	global_load_dwordx2 v[146:147], v225, s[4:5] offset:128
	s_add_u32 s4, s50, 0x23000
	s_addc_u32 s5, s51, 0
	global_load_dwordx2 v[148:149], v225, s[4:5]
	global_load_dwordx2 v[150:151], v225, s[4:5] offset:128
	s_add_u32 s4, s50, 0x30000
	s_addc_u32 s5, s51, 0
	global_load_dwordx2 v[152:153], v225, s[4:5]
	global_load_dwordx2 v[154:155], v225, s[4:5] offset:128
	s_add_u32 s4, s50, 0x31000
	s_addc_u32 s5, s51, 0
	global_load_dwordx2 v[156:157], v225, s[4:5]
	global_load_dwordx2 v[158:159], v225, s[4:5] offset:128
	s_add_u32 s4, s50, 0x32000
	s_addc_u32 s5, s51, 0
	global_load_dwordx2 v[160:161], v225, s[4:5]
	global_load_dwordx2 v[162:163], v225, s[4:5] offset:128
	s_add_u32 s4, s50, 0x33000
	s_addc_u32 s5, s51, 0
	global_load_dwordx2 v[164:165], v225, s[4:5]
	global_load_dwordx2 v[166:167], v225, s[4:5] offset:128
	s_add_u32 s4, s50, 0x40000
	s_addc_u32 s5, s51, 0
	global_load_dwordx2 v[204:205], v225, s[4:5]
	global_load_dwordx2 v[206:207], v225, s[4:5] offset:128
	s_add_u32 s4, s50, 0x41000
	s_addc_u32 s5, s51, 0
	global_load_dwordx2 v[208:209], v225, s[4:5]
	global_load_dwordx2 v[210:211], v225, s[4:5] offset:128
	s_add_u32 s4, s50, 0x42000
	s_addc_u32 s5, s51, 0
	global_load_dwordx2 v[212:213], v225, s[4:5]
	global_load_dwordx2 v[214:215], v225, s[4:5] offset:128
	s_add_u32 s4, s50, 0x43000
	s_addc_u32 s5, s51, 0
	global_load_dwordx2 v[216:217], v225, s[4:5]
	global_load_dwordx2 v[218:219], v225, s[4:5] offset:128
	s_nop 7
	s_nop 7
	v_mul_f32_e32 v96, s55, v96
	v_mul_f32_e32 v97, s55, v97
	v_mul_f32_e32 v98, s55, v98
	v_mul_f32_e32 v99, s55, v99
	v_fmac_f32_e32 v96, v226, v0
	v_fmac_f32_e32 v97, v227, v4
	v_fmac_f32_e32 v98, v228, v8
	v_fmac_f32_e32 v99, v229, v12
	v_mul_f32_e32 v100, s55, v100
	v_mul_f32_e32 v101, s55, v101
	v_mul_f32_e32 v102, s55, v102
	v_mul_f32_e32 v103, s55, v103
	v_fmac_f32_e32 v100, v226, v1
	v_fmac_f32_e32 v101, v227, v5
	v_fmac_f32_e32 v102, v228, v9
	v_fmac_f32_e32 v103, v229, v13
	v_mul_f32_e32 v104, s55, v104
	v_mul_f32_e32 v105, s55, v105
	v_mul_f32_e32 v106, s55, v106
	v_mul_f32_e32 v107, s55, v107
	v_fmac_f32_e32 v104, v226, v2
	v_fmac_f32_e32 v105, v227, v6
	v_fmac_f32_e32 v106, v228, v10
	v_fmac_f32_e32 v107, v229, v14
	v_mul_f32_e32 v108, s55, v108
	v_mul_f32_e32 v109, s55, v109
	v_mul_f32_e32 v110, s55, v110
	v_mul_f32_e32 v111, s55, v111
	v_fmac_f32_e32 v108, v226, v3
	v_fmac_f32_e32 v109, v227, v7
	v_fmac_f32_e32 v110, v228, v11
	v_fmac_f32_e32 v111, v229, v15
	s_add_u32 s4, s50, 0x0
	s_addc_u32 s5, s51, 0
	global_store_dwordx2 v225, v[96:97], s[4:5]
	global_store_dwordx2 v225, v[98:99], s[4:5] offset:128
	s_add_u32 s4, s50, 0x1000
	s_addc_u32 s5, s51, 0
	global_store_dwordx2 v225, v[100:101], s[4:5]
	global_store_dwordx2 v225, v[102:103], s[4:5] offset:128
	s_add_u32 s4, s50, 0x2000
	s_addc_u32 s5, s51, 0
	global_store_dwordx2 v225, v[104:105], s[4:5]
	global_store_dwordx2 v225, v[106:107], s[4:5] offset:128
	s_add_u32 s4, s50, 0x3000
	s_addc_u32 s5, s51, 0
	global_store_dwordx2 v225, v[108:109], s[4:5]
	global_store_dwordx2 v225, v[110:111], s[4:5] offset:128
	s_add_u32 s4, s50, 0x50000
	s_addc_u32 s5, s51, 0
	global_load_dwordx2 v[96:97], v225, s[4:5]
	global_load_dwordx2 v[98:99], v225, s[4:5] offset:128
	s_add_u32 s4, s50, 0x51000
	s_addc_u32 s5, s51, 0
	global_load_dwordx2 v[100:101], v225, s[4:5]
	global_load_dwordx2 v[102:103], v225, s[4:5] offset:128
	s_add_u32 s4, s50, 0x52000
	s_addc_u32 s5, s51, 0
	global_load_dwordx2 v[104:105], v225, s[4:5]
	global_load_dwordx2 v[106:107], v225, s[4:5] offset:128
	s_add_u32 s4, s50, 0x53000
	s_addc_u32 s5, s51, 0
	global_load_dwordx2 v[108:109], v225, s[4:5]
	global_load_dwordx2 v[110:111], v225, s[4:5] offset:128
	s_add_u32 s4, s58, 16
	s_lshr_b32 s4, s4, 12
	s_cmp_eq_u32 s4, s59
	s_cbranch_scc1 .Lfo_g1
	s_mov_b32 s59, s4
	v_mov_b32_e32 v226, v230
	v_mov_b32_e32 v227, v231
	v_mov_b32_e32 v228, v232
	v_mov_b32_e32 v229, v233

.Lfi_nob2:
	ds_read_b128 v[204:207], v222
	ds_read_b128 v[208:211], v222 offset:2048
	ds_read_b128 v[212:215], v222 offset:4096
	ds_read_b128 v[216:219], v222 offset:6144
	ds_read_b128 a[0:3], v223
	ds_read_b128 a[4:7], v223 offset:2048
	ds_read_b128 a[8:11], v223 offset:4096
	ds_read_b128 a[12:15], v223 offset:6144
	ds_read_b128 v[136:139], v220
	ds_read_b128 v[140:143], v220 offset:2048
	ds_read_b128 v[144:147], v220 offset:4096
	ds_read_b128 v[148:151], v220 offset:6144
	ds_read_b128 v[152:155], v220 offset:8192
	ds_read_b128 v[156:159], v220 offset:10240
	ds_read_b128 v[160:163], v220 offset:12288
	ds_read_b128 v[164:167], v220 offset:14336
	s_waitcnt lgkmcnt(7)
	s_setprio 1
	v_mfma_f32_16x16x32_bf16 v[0:3], v[136:139], v[204:207], v[0:3]
	v_mfma_f32_16x16x32_bf16 v[4:7], v[136:139], v[208:211], v[4:7]
	v_mfma_f32_16x16x32_bf16 v[8:11], v[136:139], v[212:215], v[8:11]
	v_mfma_f32_16x16x32_bf16 v[12:15], v[136:139], v[216:219], v[12:15]
	s_setprio 0
	ds_read_b128 v[136:139], v221
	s_waitcnt lgkmcnt(7)
	s_setprio 1
	v_mfma_f32_16x16x32_bf16 v[16:19], v[140:143], v[204:207], v[16:19]
	v_mfma_f32_16x16x32_bf16 v[20:23], v[140:143], v[208:211], v[20:23]
	v_mfma_f32_16x16x32_bf16 v[24:27], v[140:143], v[212:215], v[24:27]
	v_mfma_f32_16x16x32_bf16 v[28:31], v[140:143], v[216:219], v[28:31]
	s_setprio 0
	ds_read_b128 v[140:143], v221 offset:2048
	s_waitcnt lgkmcnt(7)
	s_setprio 1
	v_mfma_f32_16x16x32_bf16 v[32:35], v[144:147], v[204:207], v[32:35]
	v_mfma_f32_16x16x32_bf16 v[36:39], v[144:147], v[208:211], v[36:39]
	v_mfma_f32_16x16x32_bf16 v[40:43], v[144:147], v[212:215], v[40:43]
	v_mfma_f32_16x16x32_bf16 v[44:47], v[144:147], v[216:219], v[44:47]
	s_setprio 0
	ds_read_b128 v[144:147], v221 offset:4096
	s_waitcnt lgkmcnt(7)
	s_setprio 1
	v_mfma_f32_16x16x32_bf16 v[48:51], v[148:151], v[204:207], v[48:51]
	v_mfma_f32_16x16x32_bf16 v[52:55], v[148:151], v[208:211], v[52:55]
	v_mfma_f32_16x16x32_bf16 v[56:59], v[148:151], v[212:215], v[56:59]
	v_mfma_f32_16x16x32_bf16 v[60:63], v[148:151], v[216:219], v[60:63]
	s_setprio 0
	ds_read_b128 v[148:151], v221 offset:6144
	s_waitcnt lgkmcnt(7)
	s_setprio 1
	v_mfma_f32_16x16x32_bf16 v[64:67], v[152:155], v[204:207], v[64:67]
	v_mfma_f32_16x16x32_bf16 v[68:71], v[152:155], v[208:211], v[68:71]
	v_mfma_f32_16x16x32_bf16 v[72:75], v[152:155], v[212:215], v[72:75]
	v_mfma_f32_16x16x32_bf16 v[76:79], v[152:155], v[216:219], v[76:79]
	s_setprio 0
	ds_read_b128 v[152:155], v221 offset:8192
	s_waitcnt lgkmcnt(7)
	s_setprio 1
	v_mfma_f32_16x16x32_bf16 v[80:83], v[156:159], v[204:207], v[80:83]
	v_mfma_f32_16x16x32_bf16 v[84:87], v[156:159], v[208:211], v[84:87]
	v_mfma_f32_16x16x32_bf16 v[88:91], v[156:159], v[212:215], v[88:91]
	v_mfma_f32_16x16x32_bf16 v[92:95], v[156:159], v[216:219], v[92:95]
	s_setprio 0
	ds_read_b128 v[156:159], v221 offset:10240
	s_waitcnt lgkmcnt(7)
	s_setprio 1
	v_mfma_f32_16x16x32_bf16 v[96:99], v[160:163], v[204:207], v[96:99]
	v_mfma_f32_16x16x32_bf16 v[100:103], v[160:163], v[208:211], v[100:103]
	v_mfma_f32_16x16x32_bf16 v[104:107], v[160:163], v[212:215], v[104:107]
	v_mfma_f32_16x16x32_bf16 v[108:111], v[160:163], v[216:219], v[108:111]
	s_setprio 0
	ds_read_b128 v[160:163], v221 offset:12288
	s_waitcnt lgkmcnt(7)
	s_setprio 1
	v_mfma_f32_16x16x32_bf16 v[112:115], v[164:167], v[204:207], v[112:115]
	v_mfma_f32_16x16x32_bf16 v[116:119], v[164:167], v[208:211], v[116:119]
	v_mfma_f32_16x16x32_bf16 v[120:123], v[164:167], v[212:215], v[120:123]
	v_mfma_f32_16x16x32_bf16 v[124:127], v[164:167], v[216:219], v[124:127]
	s_setprio 0
	ds_read_b128 v[164:167], v221 offset:14336
	s_waitcnt lgkmcnt(0)
	s_barrier
	v_xor_b32_e32 v222, 0x4000, v222
	v_xor_b32_e32 v223, 0x4000, v223
	s_cmp_eq_u32 s53, 15
	s_cbranch_scc1 .Lfi_last
	s_setprio 1
	v_mfma_f32_16x16x32_bf16 v[0:3], v[136:139], a[0:3], v[0:3]
	s_add_u32 m0, s52, 0x0
	s_add_u32 s4, s44, 0x0
	s_addc_u32 s5, s45, 0
	global_load_lds_dwordx4 v224, s[4:5]
	v_mfma_f32_16x16x32_bf16 v[4:7], v[136:139], a[4:7], v[4:7]
	v_mfma_f32_16x16x32_bf16 v[8:11], v[136:139], a[8:11], v[8:11]
	s_add_u32 m0, s52, 0x1000
	s_add_u32 s4, s44, 0x11000
	s_addc_u32 s5, s45, 0
	global_load_lds_dwordx4 v224, s[4:5]
	v_mfma_f32_16x16x32_bf16 v[12:15], v[136:139], a[12:15], v[12:15]
	v_mfma_f32_16x16x32_bf16 v[16:19], v[140:143], a[0:3], v[16:19]
	s_add_u32 m0, s52, 0x2000
	s_add_u32 s4, s44, 0x22000
	s_addc_u32 s5, s45, 0
	global_load_lds_dwordx4 v224, s[4:5]
	v_mfma_f32_16x16x32_bf16 v[20:23], v[140:143], a[4:7], v[20:23]
	v_mfma_f32_16x16x32_bf16 v[24:27], v[140:143], a[8:11], v[24:27]
	s_add_u32 m0, s52, 0x3000
	s_add_u32 s4, s44, 0x33000
	s_addc_u32 s5, s45, 0
	global_load_lds_dwordx4 v224, s[4:5]
	v_mfma_f32_16x16x32_bf16 v[28:31], v[140:143], a[12:15], v[28:31]
	v_mfma_f32_16x16x32_bf16 v[32:35], v[144:147], a[0:3], v[32:35]
	s_add_u32 m0, s52, 0x4000
	s_add_u32 s4, s44, 0x44000
	s_addc_u32 s5, s45, 0
	global_load_lds_dwordx4 v224, s[4:5]
	v_mfma_f32_16x16x32_bf16 v[36:39], v[144:147], a[4:7], v[36:39]
	v_mfma_f32_16x16x32_bf16 v[40:43], v[144:147], a[8:11], v[40:43]
	s_add_u32 m0, s52, 0x5000
	s_add_u32 s4, s44, 0x55000
	s_addc_u32 s5, s45, 0
	global_load_lds_dwordx4 v224, s[4:5]
	v_mfma_f32_16x16x32_bf16 v[44:47], v[144:147], a[12:15], v[44:47]
	v_mfma_f32_16x16x32_bf16 v[48:51], v[148:151], a[0:3], v[48:51]
	s_add_u32 m0, s52, 0x6000
	s_add_u32 s4, s44, 0x66000
	s_addc_u32 s5, s45, 0
	global_load_lds_dwordx4 v224, s[4:5]
	v_mfma_f32_16x16x32_bf16 v[52:55], v[148:151], a[4:7], v[52:55]
	v_mfma_f32_16x16x32_bf16 v[56:59], v[148:151], a[8:11], v[56:59]
	s_add_u32 m0, s52, 0x7000
	s_add_u32 s4, s44, 0x77000
	s_addc_u32 s5, s45, 0
	global_load_lds_dwordx4 v224, s[4:5]
	v_mfma_f32_16x16x32_bf16 v[60:63], v[148:151], a[12:15], v[60:63]
	v_mfma_f32_16x16x32_bf16 v[64:67], v[152:155], a[0:3], v[64:67]
	v_mfma_f32_16x16x32_bf16 v[68:71], v[152:155], a[4:7], v[68:71]
	v_mfma_f32_16x16x32_bf16 v[72:75], v[152:155], a[8:11], v[72:75]
	v_mfma_f32_16x16x32_bf16 v[76:79], v[152:155], a[12:15], v[76:79]
	v_mfma_f32_16x16x32_bf16 v[80:83], v[156:159], a[0:3], v[80:83]
	v_mfma_f32_16x16x32_bf16 v[84:87], v[156:159], a[4:7], v[84:87]
	v_mfma_f32_16x16x32_bf16 v[88:91], v[156:159], a[8:11], v[88:91]
	v_mfma_f32_16x16x32_bf16 v[92:95], v[156:159], a[12:15], v[92:95]
	v_mfma_f32_16x16x32_bf16 v[96:99], v[160:163], a[0:3], v[96:99]
	v_mfma_f32_16x16x32_bf16 v[100:103], v[160:163], a[4:7], v[100:103]
	v_mfma_f32_16x16x32_bf16 v[104:107], v[160:163], a[8:11], v[104:107]
	v_mfma_f32_16x16x32_bf16 v[108:111], v[160:163], a[12:15], v[108:111]
	v_mfma_f32_16x16x32_bf16 v[112:115], v[164:167], a[0:3], v[112:115]
	v_mfma_f32_16x16x32_bf16 v[116:119], v[164:167], a[4:7], v[116:119]
	v_mfma_f32_16x16x32_bf16 v[120:123], v[164:167], a[8:11], v[120:123]
	v_mfma_f32_16x16x32_bf16 v[124:127], v[164:167], a[12:15], v[124:127]
	s_setprio 0
	s_add_u32 s44, s44, 0x80
	s_addc_u32 s45, s45, 0
	s_add_u32 s53, s53, 1
	s_branch .Lfi_k

.Lfi_nopf:
	s_setprio 1
	v_mfma_f32_16x16x32_bf16 v[0:3], v[136:139], a[0:3], v[0:3]
	v_mfma_f32_16x16x32_bf16 v[4:7], v[136:139], a[4:7], v[4:7]
	v_mfma_f32_16x16x32_bf16 v[8:11], v[136:139], a[8:11], v[8:11]
	v_mfma_f32_16x16x32_bf16 v[12:15], v[136:139], a[12:15], v[12:15]
	v_mfma_f32_16x16x32_bf16 v[16:19], v[140:143], a[0:3], v[16:19]
	v_mfma_f32_16x16x32_bf16 v[20:23], v[140:143], a[4:7], v[20:23]
	v_mfma_f32_16x16x32_bf16 v[24:27], v[140:143], a[8:11], v[24:27]
	v_mfma_f32_16x16x32_bf16 v[28:31], v[140:143], a[12:15], v[28:31]
	v_mfma_f32_16x16x32_bf16 v[32:35], v[144:147], a[0:3], v[32:35]
	v_mfma_f32_16x16x32_bf16 v[36:39], v[144:147], a[4:7], v[36:39]
	v_mfma_f32_16x16x32_bf16 v[40:43], v[144:147], a[8:11], v[40:43]
	v_mfma_f32_16x16x32_bf16 v[44:47], v[144:147], a[12:15], v[44:47]
	v_mfma_f32_16x16x32_bf16 v[48:51], v[148:151], a[0:3], v[48:51]
	v_mfma_f32_16x16x32_bf16 v[52:55], v[148:151], a[4:7], v[52:55]
	v_mfma_f32_16x16x32_bf16 v[56:59], v[148:151], a[8:11], v[56:59]
	v_mfma_f32_16x16x32_bf16 v[60:63], v[148:151], a[12:15], v[60:63]
	v_mfma_f32_16x16x32_bf16 v[64:67], v[152:155], a[0:3], v[64:67]
	v_mfma_f32_16x16x32_bf16 v[68:71], v[152:155], a[4:7], v[68:71]
	v_mfma_f32_16x16x32_bf16 v[72:75], v[152:155], a[8:11], v[72:75]
	v_mfma_f32_16x16x32_bf16 v[76:79], v[152:155], a[12:15], v[76:79]
	v_mfma_f32_16x16x32_bf16 v[80:83], v[156:159], a[0:3], v[80:83]
	v_mfma_f32_16x16x32_bf16 v[84:87], v[156:159], a[4:7], v[84:87]
	v_mfma_f32_16x16x32_bf16 v[88:91], v[156:159], a[8:11], v[88:91]
	v_mfma_f32_16x16x32_bf16 v[92:95], v[156:159], a[12:15], v[92:95]
	v_mfma_f32_16x16x32_bf16 v[96:99], v[160:163], a[0:3], v[96:99]
	v_mfma_f32_16x16x32_bf16 v[100:103], v[160:163], a[4:7], v[100:103]
	v_mfma_f32_16x16x32_bf16 v[104:107], v[160:163], a[8:11], v[104:107]
	v_mfma_f32_16x16x32_bf16 v[108:111], v[160:163], a[12:15], v[108:111]
	v_mfma_f32_16x16x32_bf16 v[112:115], v[164:167], a[0:3], v[112:115]
	v_mfma_f32_16x16x32_bf16 v[116:119], v[164:167], a[4:7], v[116:119]
	v_mfma_f32_16x16x32_bf16 v[120:123], v[164:167], a[8:11], v[120:123]
	v_mfma_f32_16x16x32_bf16 v[124:127], v[164:167], a[12:15], v[124:127]
	s_setprio 0
	s_nop 7
	s_nop 7
	v_mov_b32_e32 v226, s50
	v_mov_b32_e32 v227, s51
	v_add_co_u32_e32 v226, vcc, v226, v225
	s_nop 1
	v_addc_co_u32_e32 v227, vcc, 0, v227, vcc
	v_mul_f32_e32 v228, 0xbfb8aa3b, v0
	v_exp_f32_e32 v228, v228
	s_nop 0
	v_add_f32_e32 v229, 1.0, v228
	v_div_scale_f32 v230, s[4:5], v229, v229, v0
	v_rcp_f32_e32 v231, v230
	v_div_scale_f32 v232, vcc, v0, v229, v0
	v_fma_f32 v131, -v230, v231, 1.0
	v_fmac_f32_e32 v231, v131, v231
	v_mul_f32_e32 v233, v232, v231
	v_fma_f32 v131, -v230, v233, v232
	v_fmac_f32_e32 v233, v131, v231
	v_fma_f32 v230, -v230, v233, v232
	v_div_fmas_f32 v230, v230, v231, v233
	v_div_fixup_f32 v135, v230, v229, v0
	v_mul_f32_e32 v135, v8, v135
	v_mul_f32_e32 v228, 0xbfb8aa3b, v4
	v_exp_f32_e32 v228, v228
	s_nop 0
	v_add_f32_e32 v229, 1.0, v228
	v_div_scale_f32 v230, s[4:5], v229, v229, v4
	v_rcp_f32_e32 v231, v230
	v_div_scale_f32 v232, vcc, v4, v229, v4
	v_fma_f32 v131, -v230, v231, 1.0
	v_fmac_f32_e32 v231, v131, v231
	v_mul_f32_e32 v233, v232, v231
	v_fma_f32 v131, -v230, v233, v232
	v_fmac_f32_e32 v233, v131, v231
	v_fma_f32 v230, -v230, v233, v232
	v_div_fmas_f32 v230, v230, v231, v233
	v_div_fixup_f32 v133, v230, v229, v4
	v_mul_f32_e32 v133, v12, v133
	v_cvt_pk_bf16_f32 v133, v135, v133
	global_store_dword v[226:227], v133, off
	s_mov_b64 s[40:41], 0x1680
	v_lshl_add_u64 v[226:227], v[226:227], 0, s[40:41]
	v_mul_f32_e32 v228, 0xbfb8aa3b, v1
	v_exp_f32_e32 v228, v228
	s_nop 0
	v_add_f32_e32 v229, 1.0, v228
	v_div_scale_f32 v230, s[4:5], v229, v229, v1
	v_rcp_f32_e32 v231, v230
	v_div_scale_f32 v232, vcc, v1, v229, v1
	v_fma_f32 v131, -v230, v231, 1.0
	v_fmac_f32_e32 v231, v131, v231
	v_mul_f32_e32 v233, v232, v231
	v_fma_f32 v131, -v230, v233, v232
	v_fmac_f32_e32 v233, v131, v231
	v_fma_f32 v230, -v230, v233, v232
	v_div_fmas_f32 v230, v230, v231, v233
	v_div_fixup_f32 v135, v230, v229, v1
	v_mul_f32_e32 v135, v9, v135
	v_mul_f32_e32 v228, 0xbfb8aa3b, v5
	v_exp_f32_e32 v228, v228
	s_nop 0
	v_add_f32_e32 v229, 1.0, v228
	v_div_scale_f32 v230, s[4:5], v229, v229, v5
	v_rcp_f32_e32 v231, v230
	v_div_scale_f32 v232, vcc, v5, v229, v5
	v_fma_f32 v131, -v230, v231, 1.0
	v_fmac_f32_e32 v231, v131, v231
	v_mul_f32_e32 v233, v232, v231
	v_fma_f32 v131, -v230, v233, v232
	v_fmac_f32_e32 v233, v131, v231
	v_fma_f32 v230, -v230, v233, v232
	v_div_fmas_f32 v230, v230, v231, v233
	v_div_fixup_f32 v133, v230, v229, v5
	v_mul_f32_e32 v133, v13, v133
	v_cvt_pk_bf16_f32 v133, v135, v133
	global_store_dword v[226:227], v133, off
	s_mov_b64 s[40:41], 0x1680
	v_lshl_add_u64 v[226:227], v[226:227], 0, s[40:41]
	v_mul_f32_e32 v228, 0xbfb8aa3b, v2
	v_exp_f32_e32 v228, v228
	s_nop 0
	v_add_f32_e32 v229, 1.0, v228
	v_div_scale_f32 v230, s[4:5], v229, v229, v2
	v_rcp_f32_e32 v231, v230
	v_div_scale_f32 v232, vcc, v2, v229, v2
	v_fma_f32 v131, -v230, v231, 1.0
	v_fmac_f32_e32 v231, v131, v231
	v_mul_f32_e32 v233, v232, v231
	v_fma_f32 v131, -v230, v233, v232
	v_fmac_f32_e32 v233, v131, v231
	v_fma_f32 v230, -v230, v233, v232
	v_div_fmas_f32 v230, v230, v231, v233
	v_div_fixup_f32 v135, v230, v229, v2
	v_mul_f32_e32 v135, v10, v135
	v_mul_f32_e32 v228, 0xbfb8aa3b, v6
	v_exp_f32_e32 v228, v228
	s_nop 0
	v_add_f32_e32 v229, 1.0, v228
	v_div_scale_f32 v230, s[4:5], v229, v229, v6
	v_rcp_f32_e32 v231, v230
	v_div_scale_f32 v232, vcc, v6, v229, v6
	v_fma_f32 v131, -v230, v231, 1.0
	v_fmac_f32_e32 v231, v131, v231
	v_mul_f32_e32 v233, v232, v231
	v_fma_f32 v131, -v230, v233, v232
	v_fmac_f32_e32 v233, v131, v231
	v_fma_f32 v230, -v230, v233, v232
	v_div_fmas_f32 v230, v230, v231, v233
	v_div_fixup_f32 v133, v230, v229, v6
	v_mul_f32_e32 v133, v14, v133
	v_cvt_pk_bf16_f32 v133, v135, v133
	global_store_dword v[226:227], v133, off
	s_mov_b64 s[40:41], 0x1680
	v_lshl_add_u64 v[226:227], v[226:227], 0, s[40:41]
	v_mul_f32_e32 v228, 0xbfb8aa3b, v3
	v_exp_f32_e32 v228, v228
	s_nop 0
	v_add_f32_e32 v229, 1.0, v228
	v_div_scale_f32 v230, s[4:5], v229, v229, v3
	v_rcp_f32_e32 v231, v230
	v_div_scale_f32 v232, vcc, v3, v229, v3
	v_fma_f32 v131, -v230, v231, 1.0
	v_fmac_f32_e32 v231, v131, v231
	v_mul_f32_e32 v233, v232, v231
	v_fma_f32 v131, -v230, v233, v232
	v_fmac_f32_e32 v233, v131, v231
	v_fma_f32 v230, -v230, v233, v232
	v_div_fmas_f32 v230, v230, v231, v233
	v_div_fixup_f32 v135, v230, v229, v3
	v_mul_f32_e32 v135, v11, v135
	v_mul_f32_e32 v228, 0xbfb8aa3b, v7
	v_exp_f32_e32 v228, v228
	s_nop 0
	v_add_f32_e32 v229, 1.0, v228
	v_div_scale_f32 v230, s[4:5], v229, v229, v7
	v_rcp_f32_e32 v231, v230
	v_div_scale_f32 v232, vcc, v7, v229, v7
	v_fma_f32 v131, -v230, v231, 1.0
	v_fmac_f32_e32 v231, v131, v231
	v_mul_f32_e32 v233, v232, v231
	v_fma_f32 v131, -v230, v233, v232
	v_fmac_f32_e32 v233, v131, v231
	v_fma_f32 v230, -v230, v233, v232
	v_div_fmas_f32 v230, v230, v231, v233
	v_div_fixup_f32 v133, v230, v229, v7
	v_mul_f32_e32 v133, v15, v133
	v_cvt_pk_bf16_f32 v133, v135, v133
	global_store_dword v[226:227], v133, off
	s_mov_b64 s[40:41], 0x12480
	v_lshl_add_u64 v[226:227], v[226:227], 0, s[40:41]
	v_mul_f32_e32 v228, 0xbfb8aa3b, v16
	v_exp_f32_e32 v228, v228
	s_nop 0
	v_add_f32_e32 v229, 1.0, v228
	v_div_scale_f32 v230, s[4:5], v229, v229, v16
	v_rcp_f32_e32 v231, v230
	v_div_scale_f32 v232, vcc, v16, v229, v16
	v_fma_f32 v131, -v230, v231, 1.0
	v_fmac_f32_e32 v231, v131, v231
	v_mul_f32_e32 v233, v232, v231
	v_fma_f32 v131, -v230, v233, v232
	v_fmac_f32_e32 v233, v131, v231
	v_fma_f32 v230, -v230, v233, v232
	v_div_fmas_f32 v230, v230, v231, v233
	v_div_fixup_f32 v135, v230, v229, v16
	v_mul_f32_e32 v135, v24, v135
	v_mul_f32_e32 v228, 0xbfb8aa3b, v20
	v_exp_f32_e32 v228, v228
	s_nop 0
	v_add_f32_e32 v229, 1.0, v228
	v_div_scale_f32 v230, s[4:5], v229, v229, v20
	v_rcp_f32_e32 v231, v230
	v_div_scale_f32 v232, vcc, v20, v229, v20
	v_fma_f32 v131, -v230, v231, 1.0
	v_fmac_f32_e32 v231, v131, v231
	v_mul_f32_e32 v233, v232, v231
	v_fma_f32 v131, -v230, v233, v232
	v_fmac_f32_e32 v233, v131, v231
	v_fma_f32 v230, -v230, v233, v232
	v_div_fmas_f32 v230, v230, v231, v233
	v_div_fixup_f32 v133, v230, v229, v20
	v_mul_f32_e32 v133, v28, v133
	v_cvt_pk_bf16_f32 v133, v135, v133
	global_store_dword v[226:227], v133, off
	s_mov_b64 s[40:41], 0x1680
	v_lshl_add_u64 v[226:227], v[226:227], 0, s[40:41]
	v_mul_f32_e32 v228, 0xbfb8aa3b, v17
	v_exp_f32_e32 v228, v228
	s_nop 0
	v_add_f32_e32 v229, 1.0, v228
	v_div_scale_f32 v230, s[4:5], v229, v229, v17
	v_rcp_f32_e32 v231, v230
	v_div_scale_f32 v232, vcc, v17, v229, v17
	v_fma_f32 v131, -v230, v231, 1.0
	v_fmac_f32_e32 v231, v131, v231
	v_mul_f32_e32 v233, v232, v231
	v_fma_f32 v131, -v230, v233, v232
	v_fmac_f32_e32 v233, v131, v231
	v_fma_f32 v230, -v230, v233, v232
	v_div_fmas_f32 v230, v230, v231, v233
	v_div_fixup_f32 v135, v230, v229, v17
	v_mul_f32_e32 v135, v25, v135
	v_mul_f32_e32 v228, 0xbfb8aa3b, v21
	v_exp_f32_e32 v228, v228
	s_nop 0
	v_add_f32_e32 v229, 1.0, v228
	v_div_scale_f32 v230, s[4:5], v229, v229, v21
	v_rcp_f32_e32 v231, v230
	v_div_scale_f32 v232, vcc, v21, v229, v21
	v_fma_f32 v131, -v230, v231, 1.0
	v_fmac_f32_e32 v231, v131, v231
	v_mul_f32_e32 v233, v232, v231
	v_fma_f32 v131, -v230, v233, v232
	v_fmac_f32_e32 v233, v131, v231
	v_fma_f32 v230, -v230, v233, v232
	v_div_fmas_f32 v230, v230, v231, v233
	v_div_fixup_f32 v133, v230, v229, v21
	v_mul_f32_e32 v133, v29, v133
	v_cvt_pk_bf16_f32 v133, v135, v133
	global_store_dword v[226:227], v133, off
	s_mov_b64 s[40:41], 0x1680
	v_lshl_add_u64 v[226:227], v[226:227], 0, s[40:41]
	v_mul_f32_e32 v228, 0xbfb8aa3b, v18
	v_exp_f32_e32 v228, v228
	s_nop 0
	v_add_f32_e32 v229, 1.0, v228
	v_div_scale_f32 v230, s[4:5], v229, v229, v18
	v_rcp_f32_e32 v231, v230
	v_div_scale_f32 v232, vcc, v18, v229, v18
	v_fma_f32 v131, -v230, v231, 1.0
	v_fmac_f32_e32 v231, v131, v231
	v_mul_f32_e32 v233, v232, v231
	v_fma_f32 v131, -v230, v233, v232
	v_fmac_f32_e32 v233, v131, v231
	v_fma_f32 v230, -v230, v233, v232
	v_div_fmas_f32 v230, v230, v231, v233
	v_div_fixup_f32 v135, v230, v229, v18
	v_mul_f32_e32 v135, v26, v135
	v_mul_f32_e32 v228, 0xbfb8aa3b, v22
	v_exp_f32_e32 v228, v228
	s_nop 0
	v_add_f32_e32 v229, 1.0, v228
	v_div_scale_f32 v230, s[4:5], v229, v229, v22
	v_rcp_f32_e32 v231, v230
	v_div_scale_f32 v232, vcc, v22, v229, v22
	v_fma_f32 v131, -v230, v231, 1.0
	v_fmac_f32_e32 v231, v131, v231
	v_mul_f32_e32 v233, v232, v231
	v_fma_f32 v131, -v230, v233, v232
	v_fmac_f32_e32 v233, v131, v231
	v_fma_f32 v230, -v230, v233, v232
	v_div_fmas_f32 v230, v230, v231, v233
	v_div_fixup_f32 v133, v230, v229, v22
	v_mul_f32_e32 v133, v30, v133
	v_cvt_pk_bf16_f32 v133, v135, v133
	global_store_dword v[226:227], v133, off
	s_mov_b64 s[40:41], 0x1680
	v_lshl_add_u64 v[226:227], v[226:227], 0, s[40:41]
	v_mul_f32_e32 v228, 0xbfb8aa3b, v19
	v_exp_f32_e32 v228, v228
	s_nop 0
	v_add_f32_e32 v229, 1.0, v228
	v_div_scale_f32 v230, s[4:5], v229, v229, v19
	v_rcp_f32_e32 v231, v230
	v_div_scale_f32 v232, vcc, v19, v229, v19
	v_fma_f32 v131, -v230, v231, 1.0
	v_fmac_f32_e32 v231, v131, v231
	v_mul_f32_e32 v233, v232, v231
	v_fma_f32 v131, -v230, v233, v232
	v_fmac_f32_e32 v233, v131, v231
	v_fma_f32 v230, -v230, v233, v232
	v_div_fmas_f32 v230, v230, v231, v233
	v_div_fixup_f32 v135, v230, v229, v19
	v_mul_f32_e32 v135, v27, v135
	v_mul_f32_e32 v228, 0xbfb8aa3b, v23
	v_exp_f32_e32 v228, v228
	s_nop 0
	v_add_f32_e32 v229, 1.0, v228
	v_div_scale_f32 v230, s[4:5], v229, v229, v23
	v_rcp_f32_e32 v231, v230
	v_div_scale_f32 v232, vcc, v23, v229, v23
	v_fma_f32 v131, -v230, v231, 1.0
	v_fmac_f32_e32 v231, v131, v231
	v_mul_f32_e32 v233, v232, v231
	v_fma_f32 v131, -v230, v233, v232
	v_fmac_f32_e32 v233, v131, v231
	v_fma_f32 v230, -v230, v233, v232
	v_div_fmas_f32 v230, v230, v231, v233
	v_div_fixup_f32 v133, v230, v229, v23
	v_mul_f32_e32 v133, v31, v133
	v_cvt_pk_bf16_f32 v133, v135, v133
	global_store_dword v[226:227], v133, off
	s_mov_b64 s[40:41], 0x12480
	v_lshl_add_u64 v[226:227], v[226:227], 0, s[40:41]
	v_mul_f32_e32 v228, 0xbfb8aa3b, v32
	v_exp_f32_e32 v228, v228
	s_nop 0
	v_add_f32_e32 v229, 1.0, v228
	v_div_scale_f32 v230, s[4:5], v229, v229, v32
	v_rcp_f32_e32 v231, v230
	v_div_scale_f32 v232, vcc, v32, v229, v32
	v_fma_f32 v131, -v230, v231, 1.0
	v_fmac_f32_e32 v231, v131, v231
	v_mul_f32_e32 v233, v232, v231
	v_fma_f32 v131, -v230, v233, v232
	v_fmac_f32_e32 v233, v131, v231
	v_fma_f32 v230, -v230, v233, v232
	v_div_fmas_f32 v230, v230, v231, v233
	v_div_fixup_f32 v135, v230, v229, v32
	v_mul_f32_e32 v135, v40, v135
	v_mul_f32_e32 v228, 0xbfb8aa3b, v36
	v_exp_f32_e32 v228, v228
	s_nop 0
	v_add_f32_e32 v229, 1.0, v228
	v_div_scale_f32 v230, s[4:5], v229, v229, v36
	v_rcp_f32_e32 v231, v230
	v_div_scale_f32 v232, vcc, v36, v229, v36
	v_fma_f32 v131, -v230, v231, 1.0
	v_fmac_f32_e32 v231, v131, v231
	v_mul_f32_e32 v233, v232, v231
	v_fma_f32 v131, -v230, v233, v232
	v_fmac_f32_e32 v233, v131, v231
	v_fma_f32 v230, -v230, v233, v232
	v_div_fmas_f32 v230, v230, v231, v233
	v_div_fixup_f32 v133, v230, v229, v36
	v_mul_f32_e32 v133, v44, v133
	v_cvt_pk_bf16_f32 v133, v135, v133
	global_store_dword v[226:227], v133, off
	s_mov_b64 s[40:41], 0x1680
	v_lshl_add_u64 v[226:227], v[226:227], 0, s[40:41]
	v_mul_f32_e32 v228, 0xbfb8aa3b, v33
	v_exp_f32_e32 v228, v228
	s_nop 0
	v_add_f32_e32 v229, 1.0, v228
	v_div_scale_f32 v230, s[4:5], v229, v229, v33
	v_rcp_f32_e32 v231, v230
	v_div_scale_f32 v232, vcc, v33, v229, v33
	v_fma_f32 v131, -v230, v231, 1.0
	v_fmac_f32_e32 v231, v131, v231
	v_mul_f32_e32 v233, v232, v231
	v_fma_f32 v131, -v230, v233, v232
	v_fmac_f32_e32 v233, v131, v231
	v_fma_f32 v230, -v230, v233, v232
	v_div_fmas_f32 v230, v230, v231, v233
	v_div_fixup_f32 v135, v230, v229, v33
	v_mul_f32_e32 v135, v41, v135
	v_mul_f32_e32 v228, 0xbfb8aa3b, v37
	v_exp_f32_e32 v228, v228
	s_nop 0
	v_add_f32_e32 v229, 1.0, v228
	v_div_scale_f32 v230, s[4:5], v229, v229, v37
	v_rcp_f32_e32 v231, v230
	v_div_scale_f32 v232, vcc, v37, v229, v37
	v_fma_f32 v131, -v230, v231, 1.0
	v_fmac_f32_e32 v231, v131, v231
	v_mul_f32_e32 v233, v232, v231
	v_fma_f32 v131, -v230, v233, v232
	v_fmac_f32_e32 v233, v131, v231
	v_fma_f32 v230, -v230, v233, v232
	v_div_fmas_f32 v230, v230, v231, v233
	v_div_fixup_f32 v133, v230, v229, v37
	v_mul_f32_e32 v133, v45, v133
	v_cvt_pk_bf16_f32 v133, v135, v133
	global_store_dword v[226:227], v133, off
	s_mov_b64 s[40:41], 0x1680
	v_lshl_add_u64 v[226:227], v[226:227], 0, s[40:41]
	v_mul_f32_e32 v228, 0xbfb8aa3b, v34
	v_exp_f32_e32 v228, v228
	s_nop 0
	v_add_f32_e32 v229, 1.0, v228
	v_div_scale_f32 v230, s[4:5], v229, v229, v34
	v_rcp_f32_e32 v231, v230
	v_div_scale_f32 v232, vcc, v34, v229, v34
	v_fma_f32 v131, -v230, v231, 1.0
	v_fmac_f32_e32 v231, v131, v231
	v_mul_f32_e32 v233, v232, v231
	v_fma_f32 v131, -v230, v233, v232
	v_fmac_f32_e32 v233, v131, v231
	v_fma_f32 v230, -v230, v233, v232
	v_div_fmas_f32 v230, v230, v231, v233
	v_div_fixup_f32 v135, v230, v229, v34
	v_mul_f32_e32 v135, v42, v135
	v_mul_f32_e32 v228, 0xbfb8aa3b, v38
	v_exp_f32_e32 v228, v228
	s_nop 0
	v_add_f32_e32 v229, 1.0, v228
	v_div_scale_f32 v230, s[4:5], v229, v229, v38
	v_rcp_f32_e32 v231, v230
	v_div_scale_f32 v232, vcc, v38, v229, v38
	v_fma_f32 v131, -v230, v231, 1.0
	v_fmac_f32_e32 v231, v131, v231
	v_mul_f32_e32 v233, v232, v231
	v_fma_f32 v131, -v230, v233, v232
	v_fmac_f32_e32 v233, v131, v231
	v_fma_f32 v230, -v230, v233, v232
	v_div_fmas_f32 v230, v230, v231, v233
	v_div_fixup_f32 v133, v230, v229, v38
	v_mul_f32_e32 v133, v46, v133
	v_cvt_pk_bf16_f32 v133, v135, v133
	global_store_dword v[226:227], v133, off
	s_mov_b64 s[40:41], 0x1680
	v_lshl_add_u64 v[226:227], v[226:227], 0, s[40:41]
	v_mul_f32_e32 v228, 0xbfb8aa3b, v35
	v_exp_f32_e32 v228, v228
	s_nop 0
	v_add_f32_e32 v229, 1.0, v228
	v_div_scale_f32 v230, s[4:5], v229, v229, v35
	v_rcp_f32_e32 v231, v230
	v_div_scale_f32 v232, vcc, v35, v229, v35
	v_fma_f32 v131, -v230, v231, 1.0
	v_fmac_f32_e32 v231, v131, v231
	v_mul_f32_e32 v233, v232, v231
	v_fma_f32 v131, -v230, v233, v232
	v_fmac_f32_e32 v233, v131, v231
	v_fma_f32 v230, -v230, v233, v232
	v_div_fmas_f32 v230, v230, v231, v233
	v_div_fixup_f32 v135, v230, v229, v35
	v_mul_f32_e32 v135, v43, v135
	v_mul_f32_e32 v228, 0xbfb8aa3b, v39
	v_exp_f32_e32 v228, v228
	s_nop 0
	v_add_f32_e32 v229, 1.0, v228
	v_div_scale_f32 v230, s[4:5], v229, v229, v39
	v_rcp_f32_e32 v231, v230
	v_div_scale_f32 v232, vcc, v39, v229, v39
	v_fma_f32 v131, -v230, v231, 1.0
	v_fmac_f32_e32 v231, v131, v231
	v_mul_f32_e32 v233, v232, v231
	v_fma_f32 v131, -v230, v233, v232
	v_fmac_f32_e32 v233, v131, v231
	v_fma_f32 v230, -v230, v233, v232
	v_div_fmas_f32 v230, v230, v231, v233
	v_div_fixup_f32 v133, v230, v229, v39
	v_mul_f32_e32 v133, v47, v133
	v_cvt_pk_bf16_f32 v133, v135, v133
	global_store_dword v[226:227], v133, off
	s_mov_b64 s[40:41], 0x12480
	v_lshl_add_u64 v[226:227], v[226:227], 0, s[40:41]
	v_mul_f32_e32 v228, 0xbfb8aa3b, v48
	v_exp_f32_e32 v228, v228
	s_nop 0
	v_add_f32_e32 v229, 1.0, v228
	v_div_scale_f32 v230, s[4:5], v229, v229, v48
	v_rcp_f32_e32 v231, v230
	v_div_scale_f32 v232, vcc, v48, v229, v48
	v_fma_f32 v131, -v230, v231, 1.0
	v_fmac_f32_e32 v231, v131, v231
	v_mul_f32_e32 v233, v232, v231
	v_fma_f32 v131, -v230, v233, v232
	v_fmac_f32_e32 v233, v131, v231
	v_fma_f32 v230, -v230, v233, v232
	v_div_fmas_f32 v230, v230, v231, v233
	v_div_fixup_f32 v135, v230, v229, v48
	v_mul_f32_e32 v135, v56, v135
	v_mul_f32_e32 v228, 0xbfb8aa3b, v52
	v_exp_f32_e32 v228, v228
	s_nop 0
	v_add_f32_e32 v229, 1.0, v228
	v_div_scale_f32 v230, s[4:5], v229, v229, v52
	v_rcp_f32_e32 v231, v230
	v_div_scale_f32 v232, vcc, v52, v229, v52
	v_fma_f32 v131, -v230, v231, 1.0
	v_fmac_f32_e32 v231, v131, v231
	v_mul_f32_e32 v233, v232, v231
	v_fma_f32 v131, -v230, v233, v232
	v_fmac_f32_e32 v233, v131, v231
	v_fma_f32 v230, -v230, v233, v232
	v_div_fmas_f32 v230, v230, v231, v233
	v_div_fixup_f32 v133, v230, v229, v52
	v_mul_f32_e32 v133, v60, v133
	v_cvt_pk_bf16_f32 v133, v135, v133
	global_store_dword v[226:227], v133, off
	s_mov_b64 s[40:41], 0x1680
	v_lshl_add_u64 v[226:227], v[226:227], 0, s[40:41]
	v_mul_f32_e32 v228, 0xbfb8aa3b, v49
	v_exp_f32_e32 v228, v228
	s_nop 0
	v_add_f32_e32 v229, 1.0, v228
	v_div_scale_f32 v230, s[4:5], v229, v229, v49
	v_rcp_f32_e32 v231, v230
	v_div_scale_f32 v232, vcc, v49, v229, v49
	v_fma_f32 v131, -v230, v231, 1.0
	v_fmac_f32_e32 v231, v131, v231
	v_mul_f32_e32 v233, v232, v231
	v_fma_f32 v131, -v230, v233, v232
	v_fmac_f32_e32 v233, v131, v231
	v_fma_f32 v230, -v230, v233, v232
	v_div_fmas_f32 v230, v230, v231, v233
	v_div_fixup_f32 v135, v230, v229, v49
	v_mul_f32_e32 v135, v57, v135
	v_mul_f32_e32 v228, 0xbfb8aa3b, v53
	v_exp_f32_e32 v228, v228
	s_nop 0
	v_add_f32_e32 v229, 1.0, v228
	v_div_scale_f32 v230, s[4:5], v229, v229, v53
	v_rcp_f32_e32 v231, v230
	v_div_scale_f32 v232, vcc, v53, v229, v53
	v_fma_f32 v131, -v230, v231, 1.0
	v_fmac_f32_e32 v231, v131, v231
	v_mul_f32_e32 v233, v232, v231
	v_fma_f32 v131, -v230, v233, v232
	v_fmac_f32_e32 v233, v131, v231
	v_fma_f32 v230, -v230, v233, v232
	v_div_fmas_f32 v230, v230, v231, v233
	v_div_fixup_f32 v133, v230, v229, v53
	v_mul_f32_e32 v133, v61, v133
	v_cvt_pk_bf16_f32 v133, v135, v133
	global_store_dword v[226:227], v133, off
	s_mov_b64 s[40:41], 0x1680
	v_lshl_add_u64 v[226:227], v[226:227], 0, s[40:41]
	v_mul_f32_e32 v228, 0xbfb8aa3b, v50
	v_exp_f32_e32 v228, v228
	s_nop 0
	v_add_f32_e32 v229, 1.0, v228
	v_div_scale_f32 v230, s[4:5], v229, v229, v50
	v_rcp_f32_e32 v231, v230
	v_div_scale_f32 v232, vcc, v50, v229, v50
	v_fma_f32 v131, -v230, v231, 1.0
	v_fmac_f32_e32 v231, v131, v231
	v_mul_f32_e32 v233, v232, v231
	v_fma_f32 v131, -v230, v233, v232
	v_fmac_f32_e32 v233, v131, v231
	v_fma_f32 v230, -v230, v233, v232
	v_div_fmas_f32 v230, v230, v231, v233
	v_div_fixup_f32 v135, v230, v229, v50
	v_mul_f32_e32 v135, v58, v135
	v_mul_f32_e32 v228, 0xbfb8aa3b, v54
	v_exp_f32_e32 v228, v228
	s_nop 0
	v_add_f32_e32 v229, 1.0, v228
	v_div_scale_f32 v230, s[4:5], v229, v229, v54
	v_rcp_f32_e32 v231, v230
	v_div_scale_f32 v232, vcc, v54, v229, v54
	v_fma_f32 v131, -v230, v231, 1.0
	v_fmac_f32_e32 v231, v131, v231
	v_mul_f32_e32 v233, v232, v231
	v_fma_f32 v131, -v230, v233, v232
	v_fmac_f32_e32 v233, v131, v231
	v_fma_f32 v230, -v230, v233, v232
	v_div_fmas_f32 v230, v230, v231, v233
	v_div_fixup_f32 v133, v230, v229, v54
	v_mul_f32_e32 v133, v62, v133
	v_cvt_pk_bf16_f32 v133, v135, v133
	global_store_dword v[226:227], v133, off
	s_mov_b64 s[40:41], 0x1680
	v_lshl_add_u64 v[226:227], v[226:227], 0, s[40:41]
	v_mul_f32_e32 v228, 0xbfb8aa3b, v51
	v_exp_f32_e32 v228, v228
	s_nop 0
	v_add_f32_e32 v229, 1.0, v228
	v_div_scale_f32 v230, s[4:5], v229, v229, v51
	v_rcp_f32_e32 v231, v230
	v_div_scale_f32 v232, vcc, v51, v229, v51
	v_fma_f32 v131, -v230, v231, 1.0
	v_fmac_f32_e32 v231, v131, v231
	v_mul_f32_e32 v233, v232, v231
	v_fma_f32 v131, -v230, v233, v232
	v_fmac_f32_e32 v233, v131, v231
	v_fma_f32 v230, -v230, v233, v232
	v_div_fmas_f32 v230, v230, v231, v233
	v_div_fixup_f32 v135, v230, v229, v51
	v_mul_f32_e32 v135, v59, v135
	v_mul_f32_e32 v228, 0xbfb8aa3b, v55
	v_exp_f32_e32 v228, v228
	s_nop 0
	v_add_f32_e32 v229, 1.0, v228
	v_div_scale_f32 v230, s[4:5], v229, v229, v55
	v_rcp_f32_e32 v231, v230
	v_div_scale_f32 v232, vcc, v55, v229, v55
	v_fma_f32 v131, -v230, v231, 1.0
	v_fmac_f32_e32 v231, v131, v231
	v_mul_f32_e32 v233, v232, v231
	v_fma_f32 v131, -v230, v233, v232
	v_fmac_f32_e32 v233, v131, v231
	v_fma_f32 v230, -v230, v233, v232
	v_div_fmas_f32 v230, v230, v231, v233
	v_div_fixup_f32 v133, v230, v229, v55
	v_mul_f32_e32 v133, v63, v133
	v_cvt_pk_bf16_f32 v133, v135, v133
	global_store_dword v[226:227], v133, off
	s_mov_b64 s[40:41], 0x12480
	v_lshl_add_u64 v[226:227], v[226:227], 0, s[40:41]
	v_mul_f32_e32 v228, 0xbfb8aa3b, v64
	v_exp_f32_e32 v228, v228
	s_nop 0
	v_add_f32_e32 v229, 1.0, v228
	v_div_scale_f32 v230, s[4:5], v229, v229, v64
	v_rcp_f32_e32 v231, v230
	v_div_scale_f32 v232, vcc, v64, v229, v64
	v_fma_f32 v131, -v230, v231, 1.0
	v_fmac_f32_e32 v231, v131, v231
	v_mul_f32_e32 v233, v232, v231
	v_fma_f32 v131, -v230, v233, v232
	v_fmac_f32_e32 v233, v131, v231
	v_fma_f32 v230, -v230, v233, v232
	v_div_fmas_f32 v230, v230, v231, v233
	v_div_fixup_f32 v135, v230, v229, v64
	v_mul_f32_e32 v135, v72, v135
	v_mul_f32_e32 v228, 0xbfb8aa3b, v68
	v_exp_f32_e32 v228, v228
	s_nop 0
	v_add_f32_e32 v229, 1.0, v228
	v_div_scale_f32 v230, s[4:5], v229, v229, v68
	v_rcp_f32_e32 v231, v230
	v_div_scale_f32 v232, vcc, v68, v229, v68
	v_fma_f32 v131, -v230, v231, 1.0
	v_fmac_f32_e32 v231, v131, v231
	v_mul_f32_e32 v233, v232, v231
	v_fma_f32 v131, -v230, v233, v232
	v_fmac_f32_e32 v233, v131, v231
	v_fma_f32 v230, -v230, v233, v232
	v_div_fmas_f32 v230, v230, v231, v233
	v_div_fixup_f32 v133, v230, v229, v68
	v_mul_f32_e32 v133, v76, v133
	v_cvt_pk_bf16_f32 v133, v135, v133
	global_store_dword v[226:227], v133, off
	s_mov_b64 s[40:41], 0x1680
	v_lshl_add_u64 v[226:227], v[226:227], 0, s[40:41]
	v_mul_f32_e32 v228, 0xbfb8aa3b, v65
	v_exp_f32_e32 v228, v228
	s_nop 0
	v_add_f32_e32 v229, 1.0, v228
	v_div_scale_f32 v230, s[4:5], v229, v229, v65
	v_rcp_f32_e32 v231, v230
	v_div_scale_f32 v232, vcc, v65, v229, v65
	v_fma_f32 v131, -v230, v231, 1.0
	v_fmac_f32_e32 v231, v131, v231
	v_mul_f32_e32 v233, v232, v231
	v_fma_f32 v131, -v230, v233, v232
	v_fmac_f32_e32 v233, v131, v231
	v_fma_f32 v230, -v230, v233, v232
	v_div_fmas_f32 v230, v230, v231, v233
	v_div_fixup_f32 v135, v230, v229, v65
	v_mul_f32_e32 v135, v73, v135
	v_mul_f32_e32 v228, 0xbfb8aa3b, v69
	v_exp_f32_e32 v228, v228
	s_nop 0
	v_add_f32_e32 v229, 1.0, v228
	v_div_scale_f32 v230, s[4:5], v229, v229, v69
	v_rcp_f32_e32 v231, v230
	v_div_scale_f32 v232, vcc, v69, v229, v69
	v_fma_f32 v131, -v230, v231, 1.0
	v_fmac_f32_e32 v231, v131, v231
	v_mul_f32_e32 v233, v232, v231
	v_fma_f32 v131, -v230, v233, v232
	v_fmac_f32_e32 v233, v131, v231
	v_fma_f32 v230, -v230, v233, v232
	v_div_fmas_f32 v230, v230, v231, v233
	v_div_fixup_f32 v133, v230, v229, v69
	v_mul_f32_e32 v133, v77, v133
	v_cvt_pk_bf16_f32 v133, v135, v133
	global_store_dword v[226:227], v133, off
	s_mov_b64 s[40:41], 0x1680
	v_lshl_add_u64 v[226:227], v[226:227], 0, s[40:41]
	v_mul_f32_e32 v228, 0xbfb8aa3b, v66
	v_exp_f32_e32 v228, v228
	s_nop 0
	v_add_f32_e32 v229, 1.0, v228
	v_div_scale_f32 v230, s[4:5], v229, v229, v66
	v_rcp_f32_e32 v231, v230
	v_div_scale_f32 v232, vcc, v66, v229, v66
	v_fma_f32 v131, -v230, v231, 1.0
	v_fmac_f32_e32 v231, v131, v231
	v_mul_f32_e32 v233, v232, v231
	v_fma_f32 v131, -v230, v233, v232
	v_fmac_f32_e32 v233, v131, v231
	v_fma_f32 v230, -v230, v233, v232
	v_div_fmas_f32 v230, v230, v231, v233
	v_div_fixup_f32 v135, v230, v229, v66
	v_mul_f32_e32 v135, v74, v135
	v_mul_f32_e32 v228, 0xbfb8aa3b, v70
	v_exp_f32_e32 v228, v228
	s_nop 0
	v_add_f32_e32 v229, 1.0, v228
	v_div_scale_f32 v230, s[4:5], v229, v229, v70
	v_rcp_f32_e32 v231, v230
	v_div_scale_f32 v232, vcc, v70, v229, v70
	v_fma_f32 v131, -v230, v231, 1.0
	v_fmac_f32_e32 v231, v131, v231
	v_mul_f32_e32 v233, v232, v231
	v_fma_f32 v131, -v230, v233, v232
	v_fmac_f32_e32 v233, v131, v231
	v_fma_f32 v230, -v230, v233, v232
	v_div_fmas_f32 v230, v230, v231, v233
	v_div_fixup_f32 v133, v230, v229, v70
	v_mul_f32_e32 v133, v78, v133
	v_cvt_pk_bf16_f32 v133, v135, v133
	global_store_dword v[226:227], v133, off
	s_mov_b64 s[40:41], 0x1680
	v_lshl_add_u64 v[226:227], v[226:227], 0, s[40:41]
	v_mul_f32_e32 v228, 0xbfb8aa3b, v67
	v_exp_f32_e32 v228, v228
	s_nop 0
	v_add_f32_e32 v229, 1.0, v228
	v_div_scale_f32 v230, s[4:5], v229, v229, v67
	v_rcp_f32_e32 v231, v230
	v_div_scale_f32 v232, vcc, v67, v229, v67
	v_fma_f32 v131, -v230, v231, 1.0
	v_fmac_f32_e32 v231, v131, v231
	v_mul_f32_e32 v233, v232, v231
	v_fma_f32 v131, -v230, v233, v232
	v_fmac_f32_e32 v233, v131, v231
	v_fma_f32 v230, -v230, v233, v232
	v_div_fmas_f32 v230, v230, v231, v233
	v_div_fixup_f32 v135, v230, v229, v67
	v_mul_f32_e32 v135, v75, v135
	v_mul_f32_e32 v228, 0xbfb8aa3b, v71
	v_exp_f32_e32 v228, v228
	s_nop 0
	v_add_f32_e32 v229, 1.0, v228
	v_div_scale_f32 v230, s[4:5], v229, v229, v71
	v_rcp_f32_e32 v231, v230
	v_div_scale_f32 v232, vcc, v71, v229, v71
	v_fma_f32 v131, -v230, v231, 1.0
	v_fmac_f32_e32 v231, v131, v231
	v_mul_f32_e32 v233, v232, v231
	v_fma_f32 v131, -v230, v233, v232
	v_fmac_f32_e32 v233, v131, v231
	v_fma_f32 v230, -v230, v233, v232
	v_div_fmas_f32 v230, v230, v231, v233
	v_div_fixup_f32 v133, v230, v229, v71
	v_mul_f32_e32 v133, v79, v133
	v_cvt_pk_bf16_f32 v133, v135, v133
	global_store_dword v[226:227], v133, off
	s_mov_b64 s[40:41], 0x12480
	v_lshl_add_u64 v[226:227], v[226:227], 0, s[40:41]
	v_mul_f32_e32 v228, 0xbfb8aa3b, v80
	v_exp_f32_e32 v228, v228
	s_nop 0
	v_add_f32_e32 v229, 1.0, v228
	v_div_scale_f32 v230, s[4:5], v229, v229, v80
	v_rcp_f32_e32 v231, v230
	v_div_scale_f32 v232, vcc, v80, v229, v80
	v_fma_f32 v131, -v230, v231, 1.0
	v_fmac_f32_e32 v231, v131, v231
	v_mul_f32_e32 v233, v232, v231
	v_fma_f32 v131, -v230, v233, v232
	v_fmac_f32_e32 v233, v131, v231
	v_fma_f32 v230, -v230, v233, v232
	v_div_fmas_f32 v230, v230, v231, v233
	v_div_fixup_f32 v135, v230, v229, v80
	v_mul_f32_e32 v135, v88, v135
	v_mul_f32_e32 v228, 0xbfb8aa3b, v84
	v_exp_f32_e32 v228, v228
	s_nop 0
	v_add_f32_e32 v229, 1.0, v228
	v_div_scale_f32 v230, s[4:5], v229, v229, v84
	v_rcp_f32_e32 v231, v230
	v_div_scale_f32 v232, vcc, v84, v229, v84
	v_fma_f32 v131, -v230, v231, 1.0
	v_fmac_f32_e32 v231, v131, v231
	v_mul_f32_e32 v233, v232, v231
	v_fma_f32 v131, -v230, v233, v232
	v_fmac_f32_e32 v233, v131, v231
	v_fma_f32 v230, -v230, v233, v232
	v_div_fmas_f32 v230, v230, v231, v233
	v_div_fixup_f32 v133, v230, v229, v84
	v_mul_f32_e32 v133, v92, v133
	v_cvt_pk_bf16_f32 v133, v135, v133
	global_store_dword v[226:227], v133, off
	s_mov_b64 s[40:41], 0x1680
	v_lshl_add_u64 v[226:227], v[226:227], 0, s[40:41]
	v_mul_f32_e32 v228, 0xbfb8aa3b, v81
	v_exp_f32_e32 v228, v228
	s_nop 0
	v_add_f32_e32 v229, 1.0, v228
	v_div_scale_f32 v230, s[4:5], v229, v229, v81
	v_rcp_f32_e32 v231, v230
	v_div_scale_f32 v232, vcc, v81, v229, v81
	v_fma_f32 v131, -v230, v231, 1.0
	v_fmac_f32_e32 v231, v131, v231
	v_mul_f32_e32 v233, v232, v231
	v_fma_f32 v131, -v230, v233, v232
	v_fmac_f32_e32 v233, v131, v231
	v_fma_f32 v230, -v230, v233, v232
	v_div_fmas_f32 v230, v230, v231, v233
	v_div_fixup_f32 v135, v230, v229, v81
	v_mul_f32_e32 v135, v89, v135
	v_mul_f32_e32 v228, 0xbfb8aa3b, v85
	v_exp_f32_e32 v228, v228
	s_nop 0
	v_add_f32_e32 v229, 1.0, v228
	v_div_scale_f32 v230, s[4:5], v229, v229, v85
	v_rcp_f32_e32 v231, v230
	v_div_scale_f32 v232, vcc, v85, v229, v85
	v_fma_f32 v131, -v230, v231, 1.0
	v_fmac_f32_e32 v231, v131, v231
	v_mul_f32_e32 v233, v232, v231
	v_fma_f32 v131, -v230, v233, v232
	v_fmac_f32_e32 v233, v131, v231
	v_fma_f32 v230, -v230, v233, v232
	v_div_fmas_f32 v230, v230, v231, v233
	v_div_fixup_f32 v133, v230, v229, v85
	v_mul_f32_e32 v133, v93, v133
	v_cvt_pk_bf16_f32 v133, v135, v133
	global_store_dword v[226:227], v133, off
	s_mov_b64 s[40:41], 0x1680
	v_lshl_add_u64 v[226:227], v[226:227], 0, s[40:41]
	v_mul_f32_e32 v228, 0xbfb8aa3b, v82
	v_exp_f32_e32 v228, v228
	s_nop 0
	v_add_f32_e32 v229, 1.0, v228
	v_div_scale_f32 v230, s[4:5], v229, v229, v82
	v_rcp_f32_e32 v231, v230
	v_div_scale_f32 v232, vcc, v82, v229, v82
	v_fma_f32 v131, -v230, v231, 1.0
	v_fmac_f32_e32 v231, v131, v231
	v_mul_f32_e32 v233, v232, v231
	v_fma_f32 v131, -v230, v233, v232
	v_fmac_f32_e32 v233, v131, v231
	v_fma_f32 v230, -v230, v233, v232
	v_div_fmas_f32 v230, v230, v231, v233
	v_div_fixup_f32 v135, v230, v229, v82
	v_mul_f32_e32 v135, v90, v135
	v_mul_f32_e32 v228, 0xbfb8aa3b, v86
	v_exp_f32_e32 v228, v228
	s_nop 0
	v_add_f32_e32 v229, 1.0, v228
	v_div_scale_f32 v230, s[4:5], v229, v229, v86
	v_rcp_f32_e32 v231, v230
	v_div_scale_f32 v232, vcc, v86, v229, v86
	v_fma_f32 v131, -v230, v231, 1.0
	v_fmac_f32_e32 v231, v131, v231
	v_mul_f32_e32 v233, v232, v231
	v_fma_f32 v131, -v230, v233, v232
	v_fmac_f32_e32 v233, v131, v231
	v_fma_f32 v230, -v230, v233, v232
	v_div_fmas_f32 v230, v230, v231, v233
	v_div_fixup_f32 v133, v230, v229, v86
	v_mul_f32_e32 v133, v94, v133
	v_cvt_pk_bf16_f32 v133, v135, v133
	global_store_dword v[226:227], v133, off
	s_mov_b64 s[40:41], 0x1680
	v_lshl_add_u64 v[226:227], v[226:227], 0, s[40:41]
	v_mul_f32_e32 v228, 0xbfb8aa3b, v83
	v_exp_f32_e32 v228, v228
	s_nop 0
	v_add_f32_e32 v229, 1.0, v228
	v_div_scale_f32 v230, s[4:5], v229, v229, v83
	v_rcp_f32_e32 v231, v230
	v_div_scale_f32 v232, vcc, v83, v229, v83
	v_fma_f32 v131, -v230, v231, 1.0
	v_fmac_f32_e32 v231, v131, v231
	v_mul_f32_e32 v233, v232, v231
	v_fma_f32 v131, -v230, v233, v232
	v_fmac_f32_e32 v233, v131, v231
	v_fma_f32 v230, -v230, v233, v232
	v_div_fmas_f32 v230, v230, v231, v233
	v_div_fixup_f32 v135, v230, v229, v83
	v_mul_f32_e32 v135, v91, v135
	v_mul_f32_e32 v228, 0xbfb8aa3b, v87
	v_exp_f32_e32 v228, v228
	s_nop 0
	v_add_f32_e32 v229, 1.0, v228
	v_div_scale_f32 v230, s[4:5], v229, v229, v87
	v_rcp_f32_e32 v231, v230
	v_div_scale_f32 v232, vcc, v87, v229, v87
	v_fma_f32 v131, -v230, v231, 1.0
	v_fmac_f32_e32 v231, v131, v231
	v_mul_f32_e32 v233, v232, v231
	v_fma_f32 v131, -v230, v233, v232
	v_fmac_f32_e32 v233, v131, v231
	v_fma_f32 v230, -v230, v233, v232
	v_div_fmas_f32 v230, v230, v231, v233
	v_div_fixup_f32 v133, v230, v229, v87
	v_mul_f32_e32 v133, v95, v133
	v_cvt_pk_bf16_f32 v133, v135, v133
	global_store_dword v[226:227], v133, off
	s_mov_b64 s[40:41], 0x12480
	v_lshl_add_u64 v[226:227], v[226:227], 0, s[40:41]
	v_mul_f32_e32 v228, 0xbfb8aa3b, v96
	v_exp_f32_e32 v228, v228
	s_nop 0
	v_add_f32_e32 v229, 1.0, v228
	v_div_scale_f32 v230, s[4:5], v229, v229, v96
	v_rcp_f32_e32 v231, v230
	v_div_scale_f32 v232, vcc, v96, v229, v96
	v_fma_f32 v131, -v230, v231, 1.0
	v_fmac_f32_e32 v231, v131, v231
	v_mul_f32_e32 v233, v232, v231
	v_fma_f32 v131, -v230, v233, v232
	v_fmac_f32_e32 v233, v131, v231
	v_fma_f32 v230, -v230, v233, v232
	v_div_fmas_f32 v230, v230, v231, v233
	v_div_fixup_f32 v135, v230, v229, v96
	v_mul_f32_e32 v135, v104, v135
	v_mul_f32_e32 v228, 0xbfb8aa3b, v100
	v_exp_f32_e32 v228, v228
	s_nop 0
	v_add_f32_e32 v229, 1.0, v228
	v_div_scale_f32 v230, s[4:5], v229, v229, v100
	v_rcp_f32_e32 v231, v230
	v_div_scale_f32 v232, vcc, v100, v229, v100
	v_fma_f32 v131, -v230, v231, 1.0
	v_fmac_f32_e32 v231, v131, v231
	v_mul_f32_e32 v233, v232, v231
	v_fma_f32 v131, -v230, v233, v232
	v_fmac_f32_e32 v233, v131, v231
	v_fma_f32 v230, -v230, v233, v232
	v_div_fmas_f32 v230, v230, v231, v233
	v_div_fixup_f32 v133, v230, v229, v100
	v_mul_f32_e32 v133, v108, v133
	v_cvt_pk_bf16_f32 v133, v135, v133
	global_store_dword v[226:227], v133, off
	s_mov_b64 s[40:41], 0x1680
	v_lshl_add_u64 v[226:227], v[226:227], 0, s[40:41]
	v_mul_f32_e32 v228, 0xbfb8aa3b, v97
	v_exp_f32_e32 v228, v228
	s_nop 0
	v_add_f32_e32 v229, 1.0, v228
	v_div_scale_f32 v230, s[4:5], v229, v229, v97
	v_rcp_f32_e32 v231, v230
	v_div_scale_f32 v232, vcc, v97, v229, v97
	v_fma_f32 v131, -v230, v231, 1.0
	v_fmac_f32_e32 v231, v131, v231
	v_mul_f32_e32 v233, v232, v231
	v_fma_f32 v131, -v230, v233, v232
	v_fmac_f32_e32 v233, v131, v231
	v_fma_f32 v230, -v230, v233, v232
	v_div_fmas_f32 v230, v230, v231, v233
	v_div_fixup_f32 v135, v230, v229, v97
	v_mul_f32_e32 v135, v105, v135
	v_mul_f32_e32 v228, 0xbfb8aa3b, v101
	v_exp_f32_e32 v228, v228
	s_nop 0
	v_add_f32_e32 v229, 1.0, v228
	v_div_scale_f32 v230, s[4:5], v229, v229, v101
	v_rcp_f32_e32 v231, v230
	v_div_scale_f32 v232, vcc, v101, v229, v101
	v_fma_f32 v131, -v230, v231, 1.0
	v_fmac_f32_e32 v231, v131, v231
	v_mul_f32_e32 v233, v232, v231
	v_fma_f32 v131, -v230, v233, v232
	v_fmac_f32_e32 v233, v131, v231
	v_fma_f32 v230, -v230, v233, v232
	v_div_fmas_f32 v230, v230, v231, v233
	v_div_fixup_f32 v133, v230, v229, v101
	v_mul_f32_e32 v133, v109, v133
	v_cvt_pk_bf16_f32 v133, v135, v133
	global_store_dword v[226:227], v133, off
	s_mov_b64 s[40:41], 0x1680
	v_lshl_add_u64 v[226:227], v[226:227], 0, s[40:41]
	v_mul_f32_e32 v228, 0xbfb8aa3b, v98
	v_exp_f32_e32 v228, v228
	s_nop 0
	v_add_f32_e32 v229, 1.0, v228
	v_div_scale_f32 v230, s[4:5], v229, v229, v98
	v_rcp_f32_e32 v231, v230
	v_div_scale_f32 v232, vcc, v98, v229, v98
	v_fma_f32 v131, -v230, v231, 1.0
	v_fmac_f32_e32 v231, v131, v231
	v_mul_f32_e32 v233, v232, v231
	v_fma_f32 v131, -v230, v233, v232
	v_fmac_f32_e32 v233, v131, v231
	v_fma_f32 v230, -v230, v233, v232
	v_div_fmas_f32 v230, v230, v231, v233
	v_div_fixup_f32 v135, v230, v229, v98
	v_mul_f32_e32 v135, v106, v135
	v_mul_f32_e32 v228, 0xbfb8aa3b, v102
	v_exp_f32_e32 v228, v228
	s_nop 0
	v_add_f32_e32 v229, 1.0, v228
	v_div_scale_f32 v230, s[4:5], v229, v229, v102
	v_rcp_f32_e32 v231, v230
	v_div_scale_f32 v232, vcc, v102, v229, v102
	v_fma_f32 v131, -v230, v231, 1.0
	v_fmac_f32_e32 v231, v131, v231
	v_mul_f32_e32 v233, v232, v231
	v_fma_f32 v131, -v230, v233, v232
	v_fmac_f32_e32 v233, v131, v231
	v_fma_f32 v230, -v230, v233, v232
	v_div_fmas_f32 v230, v230, v231, v233
	v_div_fixup_f32 v133, v230, v229, v102
	v_mul_f32_e32 v133, v110, v133
	v_cvt_pk_bf16_f32 v133, v135, v133
	global_store_dword v[226:227], v133, off
	s_mov_b64 s[40:41], 0x1680
	v_lshl_add_u64 v[226:227], v[226:227], 0, s[40:41]
	v_mul_f32_e32 v228, 0xbfb8aa3b, v99
	v_exp_f32_e32 v228, v228
	s_nop 0
	v_add_f32_e32 v229, 1.0, v228
	v_div_scale_f32 v230, s[4:5], v229, v229, v99
	v_rcp_f32_e32 v231, v230
	v_div_scale_f32 v232, vcc, v99, v229, v99
	v_fma_f32 v131, -v230, v231, 1.0
	v_fmac_f32_e32 v231, v131, v231
	v_mul_f32_e32 v233, v232, v231
	v_fma_f32 v131, -v230, v233, v232
	v_fmac_f32_e32 v233, v131, v231
	v_fma_f32 v230, -v230, v233, v232
	v_div_fmas_f32 v230, v230, v231, v233
	v_div_fixup_f32 v135, v230, v229, v99
	v_mul_f32_e32 v135, v107, v135
	v_mul_f32_e32 v228, 0xbfb8aa3b, v103
	v_exp_f32_e32 v228, v228
	s_nop 0
	v_add_f32_e32 v229, 1.0, v228
	v_div_scale_f32 v230, s[4:5], v229, v229, v103
	v_rcp_f32_e32 v231, v230
	v_div_scale_f32 v232, vcc, v103, v229, v103
	v_fma_f32 v131, -v230, v231, 1.0
	v_fmac_f32_e32 v231, v131, v231
	v_mul_f32_e32 v233, v232, v231
	v_fma_f32 v131, -v230, v233, v232
	v_fmac_f32_e32 v233, v131, v231
	v_fma_f32 v230, -v230, v233, v232
	v_div_fmas_f32 v230, v230, v231, v233
	v_div_fixup_f32 v133, v230, v229, v103
	v_mul_f32_e32 v133, v111, v133
	v_cvt_pk_bf16_f32 v133, v135, v133
	global_store_dword v[226:227], v133, off
	s_mov_b64 s[40:41], 0x12480
	v_lshl_add_u64 v[226:227], v[226:227], 0, s[40:41]
	v_mul_f32_e32 v228, 0xbfb8aa3b, v112
	v_exp_f32_e32 v228, v228
	s_nop 0
	v_add_f32_e32 v229, 1.0, v228
	v_div_scale_f32 v230, s[4:5], v229, v229, v112
	v_rcp_f32_e32 v231, v230
	v_div_scale_f32 v232, vcc, v112, v229, v112
	v_fma_f32 v131, -v230, v231, 1.0
	v_fmac_f32_e32 v231, v131, v231
	v_mul_f32_e32 v233, v232, v231
	v_fma_f32 v131, -v230, v233, v232
	v_fmac_f32_e32 v233, v131, v231
	v_fma_f32 v230, -v230, v233, v232
	v_div_fmas_f32 v230, v230, v231, v233
	v_div_fixup_f32 v135, v230, v229, v112
	v_mul_f32_e32 v135, v120, v135
	v_mul_f32_e32 v228, 0xbfb8aa3b, v116
	v_exp_f32_e32 v228, v228
	s_nop 0
	v_add_f32_e32 v229, 1.0, v228
	v_div_scale_f32 v230, s[4:5], v229, v229, v116
	v_rcp_f32_e32 v231, v230
	v_div_scale_f32 v232, vcc, v116, v229, v116
	v_fma_f32 v131, -v230, v231, 1.0
	v_fmac_f32_e32 v231, v131, v231
	v_mul_f32_e32 v233, v232, v231
	v_fma_f32 v131, -v230, v233, v232
	v_fmac_f32_e32 v233, v131, v231
	v_fma_f32 v230, -v230, v233, v232
	v_div_fmas_f32 v230, v230, v231, v233
	v_div_fixup_f32 v133, v230, v229, v116
	v_mul_f32_e32 v133, v124, v133
	v_cvt_pk_bf16_f32 v133, v135, v133
	global_store_dword v[226:227], v133, off
	s_mov_b64 s[40:41], 0x1680
	v_lshl_add_u64 v[226:227], v[226:227], 0, s[40:41]
	v_mul_f32_e32 v228, 0xbfb8aa3b, v113
	v_exp_f32_e32 v228, v228
	s_nop 0
	v_add_f32_e32 v229, 1.0, v228
	v_div_scale_f32 v230, s[4:5], v229, v229, v113
	v_rcp_f32_e32 v231, v230
	v_div_scale_f32 v232, vcc, v113, v229, v113
	v_fma_f32 v131, -v230, v231, 1.0
	v_fmac_f32_e32 v231, v131, v231
	v_mul_f32_e32 v233, v232, v231
	v_fma_f32 v131, -v230, v233, v232
	v_fmac_f32_e32 v233, v131, v231
	v_fma_f32 v230, -v230, v233, v232
	v_div_fmas_f32 v230, v230, v231, v233
	v_div_fixup_f32 v135, v230, v229, v113
	v_mul_f32_e32 v135, v121, v135
	v_mul_f32_e32 v228, 0xbfb8aa3b, v117
	v_exp_f32_e32 v228, v228
	s_nop 0
	v_add_f32_e32 v229, 1.0, v228
	v_div_scale_f32 v230, s[4:5], v229, v229, v117
	v_rcp_f32_e32 v231, v230
	v_div_scale_f32 v232, vcc, v117, v229, v117
	v_fma_f32 v131, -v230, v231, 1.0
	v_fmac_f32_e32 v231, v131, v231
	v_mul_f32_e32 v233, v232, v231
	v_fma_f32 v131, -v230, v233, v232
	v_fmac_f32_e32 v233, v131, v231
	v_fma_f32 v230, -v230, v233, v232
	v_div_fmas_f32 v230, v230, v231, v233
	v_div_fixup_f32 v133, v230, v229, v117
	v_mul_f32_e32 v133, v125, v133
	v_cvt_pk_bf16_f32 v133, v135, v133
	global_store_dword v[226:227], v133, off
	s_mov_b64 s[40:41], 0x1680
	v_lshl_add_u64 v[226:227], v[226:227], 0, s[40:41]
	v_mul_f32_e32 v228, 0xbfb8aa3b, v114
	v_exp_f32_e32 v228, v228
	s_nop 0
	v_add_f32_e32 v229, 1.0, v228
	v_div_scale_f32 v230, s[4:5], v229, v229, v114
	v_rcp_f32_e32 v231, v230
	v_div_scale_f32 v232, vcc, v114, v229, v114
	v_fma_f32 v131, -v230, v231, 1.0
	v_fmac_f32_e32 v231, v131, v231
	v_mul_f32_e32 v233, v232, v231
	v_fma_f32 v131, -v230, v233, v232
	v_fmac_f32_e32 v233, v131, v231
	v_fma_f32 v230, -v230, v233, v232
	v_div_fmas_f32 v230, v230, v231, v233
	v_div_fixup_f32 v135, v230, v229, v114
	v_mul_f32_e32 v135, v122, v135
	v_mul_f32_e32 v228, 0xbfb8aa3b, v118
	v_exp_f32_e32 v228, v228
	s_nop 0
	v_add_f32_e32 v229, 1.0, v228
	v_div_scale_f32 v230, s[4:5], v229, v229, v118
	v_rcp_f32_e32 v231, v230
	v_div_scale_f32 v232, vcc, v118, v229, v118
	v_fma_f32 v131, -v230, v231, 1.0
	v_fmac_f32_e32 v231, v131, v231
	v_mul_f32_e32 v233, v232, v231
	v_fma_f32 v131, -v230, v233, v232
	v_fmac_f32_e32 v233, v131, v231
	v_fma_f32 v230, -v230, v233, v232
	v_div_fmas_f32 v230, v230, v231, v233
	v_div_fixup_f32 v133, v230, v229, v118
	v_mul_f32_e32 v133, v126, v133
	v_cvt_pk_bf16_f32 v133, v135, v133
	global_store_dword v[226:227], v133, off
	s_mov_b64 s[40:41], 0x1680
	v_lshl_add_u64 v[226:227], v[226:227], 0, s[40:41]
	v_mul_f32_e32 v228, 0xbfb8aa3b, v115
	v_exp_f32_e32 v228, v228
	s_nop 0
	v_add_f32_e32 v229, 1.0, v228
	v_div_scale_f32 v230, s[4:5], v229, v229, v115
	v_rcp_f32_e32 v231, v230
	v_div_scale_f32 v232, vcc, v115, v229, v115
	v_fma_f32 v131, -v230, v231, 1.0
	v_fmac_f32_e32 v231, v131, v231
	v_mul_f32_e32 v233, v232, v231
	v_fma_f32 v131, -v230, v233, v232
	v_fmac_f32_e32 v233, v131, v231
	v_fma_f32 v230, -v230, v233, v232
	v_div_fmas_f32 v230, v230, v231, v233
	v_div_fixup_f32 v135, v230, v229, v115
	v_mul_f32_e32 v135, v123, v135
	v_mul_f32_e32 v228, 0xbfb8aa3b, v119
	v_exp_f32_e32 v228, v228
	s_nop 0
	v_add_f32_e32 v229, 1.0, v228
	v_div_scale_f32 v230, s[4:5], v229, v229, v119
	v_rcp_f32_e32 v231, v230
	v_div_scale_f32 v232, vcc, v119, v229, v119
	v_fma_f32 v131, -v230, v231, 1.0
	v_fmac_f32_e32 v231, v131, v231
	v_mul_f32_e32 v233, v232, v231
	v_fma_f32 v131, -v230, v233, v232
	v_fmac_f32_e32 v233, v131, v231
	v_fma_f32 v230, -v230, v233, v232
	v_div_fmas_f32 v230, v230, v231, v233
	v_div_fixup_f32 v133, v230, v229, v119
	v_mul_f32_e32 v133, v127, v133
	v_cvt_pk_bf16_f32 v133, v135, v133
	global_store_dword v[226:227], v133, off
	v_readlane_b32 s40, v239, 0
	s_cmp_ge_u32 s54, s40
	s_cbranch_scc1 .Lfi_main_done
	s_lshr_b32 s55, s54, 4
	s_mul_hi_u32 s55, s55, 0x55555556
	s_mul_i32 s53, s55, 48
	s_sub_u32 s53, s54, s53
	v_readlane_b32 s4, v235, 34
	v_readlane_b32 s5, v235, 35
	s_mul_i32 s50, s53, 0x168000
	s_lshl_b32 s55, s55, 7
	s_add_u32 s50, s50, s55
	s_add_u32 s50, s50, 0xfae6000
	s_add_u32 s50, s50, s4
	s_addc_u32 s51, s5, 0
	s_branch .Lfi_tile
